# phase C epilogue rewritten: residual tile via LDS with fully coalesced row loads/stores, all table loads batched
# speedup vs baseline: 1.0644x; 1.0236x over previous
; template <bool HN, bool L0>
; DI void phaseC_epi(const Params& p, f32x4 (&acc)[2][2][4][2], int l, int n0, int m0) {
;   const int tid = get_tid(), lane = tid & 63, wid = tid >> 6, wr = wid >> 2, wc = wid & 3, fr = lane & 15, fq = lane >> 4;
;   const bool is_ctx = m0 >= NLAT;
;   const int modrow = is_ctx ? 16 : (m0 / SEQ);
;   const float* xin0 = is_ctx ? p.ctx : p.x;
;   const int rowoff = is_ctx ? NLAT : 0;
;   int tok[4];
; #pragma unroll
;   for (int g = 0; g < 4; ++g) tok[g] = m0 + (g >> 1) * 128 + wc * 32 + (g & 1) * 16 + fr;
;   {
;     const float* gatep = p.mod + (size_t)(l * 17 + modrow) * 3072 + 2048 + n0 + wr * 64 + fq * 4;
;     f32x4 gt[2][4];
; #pragma unroll
;     for (int ai = 0; ai < 2; ++ai)
; #pragma unroll
;       for (int m = 0; m < 4; ++m) gt[ai][m] = *(const f32x4*)(gatep + ai * 128 + m * 16);
; #pragma unroll
;     for (int ai = 0; ai < 2; ++ai)
; #pragma unroll
;       for (int g = 0; g < 4; ++g)
; #pragma unroll
;         for (int m = 0; m < 4; ++m)
; #pragma unroll
;           for (int j = 0; j < 4; ++j) acc[ai][g >> 1][m][g & 1][j] *= gt[ai][m][j];
;   }
;   __builtin_amdgcn_sched_barrier(0);
; #pragma unroll
;   for (int ai = 0; ai < 2; ++ai) {
;     const int f0 = n0 + ai * 128 + wr * 64 + fq * 4;
;     f32x4 gs[4], rgs[4];
; #pragma unroll
;     for (int m = 0; m < 4; ++m) {
;       if (!L0) {
;         const f32x4 g0 = *(const f32x4*)(p.norm_gain + (size_t)l * DM + f0 + m * 16);
;         const f32x4 s0 = *(const f32x4*)(p.mod + (size_t)(l * 17 + modrow) * 3072 + 1024 + f0 + m * 16);
; #pragma unroll
;         for (int j = 0; j < 4; ++j) rgs[m][j] = __builtin_amdgcn_rcpf(g0[j] * (1.f + s0[j]));
;       }
;       if (HN) {
;         const f32x4 g1 = *(const f32x4*)(p.norm_gain + (size_t)(l + 1) * DM + f0 + m * 16);
;         const f32x4 s1 = *(const f32x4*)(p.mod + (size_t)((l + 1) * 17 + modrow) * 3072 + 1024 + f0 + m * 16);
; #pragma unroll
;         for (int j = 0; j < 4; ++j) gs[m][j] = g1[j] * (1.f + s1[j]);
;       }
;     }
; #pragma unroll
;     for (int gp = 0; gp < 2; ++gp) {
;       f32x4 xv[2][4];
;       u32x2 xb[2][4];
; #pragma unroll
;       for (int n = 0; n < 2; ++n)
; #pragma unroll
;         for (int m = 0; m < 4; ++m) {
;           if (L0) xv[n][m] = *(const f32x4*)(xin0 + (size_t)(tok[gp * 2 + n] - rowoff) * DM + f0 + m * 16);
.LBB0_310:
	s_or_b64 exec, exec, s[2:3]
	v_readlane_b32 s8, v255, 3
	s_mov_b64 s[14:15], s[80:81]
	s_barrier
	s_cmp_gt_i32 s8, 2
	s_cbranch_scc1 .Lpc_last
	s_load_dwordx2 s[4:5], s[14:15], 0x20
	s_load_dwordx2 s[6:7], s[14:15], 0xa0
	s_load_dwordx2 s[10:11], s[14:15], 0xc8
	s_load_dwordx2 s[18:19], s[14:15], 0xe8
	v_bfe_u32 v0, v251, 8, 1
	v_bfe_u32 v230, v251, 4, 2
	v_lshlrev_b32_e32 v227, 4, v230
	v_lshl_or_b32 v227, v0, 8, v227
	v_lshrrev_b32_e32 v231, 5, v251
	v_and_b32_e32 v232, 31, v251
	v_xor_b32_e32 v232, v232, v231
	v_lshlrev_b32_e32 v228, 4, v232
	v_lshl_or_b32 v228, v231, 11, v228
	s_lshr_b32 s0, s26, 3
	s_cmp_gt_i32 s26, 0x7f
	s_cselect_b32 s0, 16, s0
	s_mul_i32 s9, s8, 17
	s_add_i32 s0, s0, s9
	s_mul_i32 s0, s0, 0x3000
	s_lshl_b32 s9, s25, 10
	s_add_u32 s0, s0, s9
	s_lshl_b32 s27, s8, 12
	s_add_u32 s27, s27, s9
	s_lshl_b32 s28, s26, 19
	s_lshl_b32 s9, s25, 9
	s_add_u32 s28, s28, s9
	s_mov_b32 s2, 0xffff
	s_mov_b32 s3, 0
	v_readfirstlane_b32 s9, v251
	s_waitcnt lgkmcnt(0)
	s_add_u32 s10, s10, s0
	s_addc_u32 s11, s11, 0
	s_add_u32 s4, s4, s27
	s_addc_u32 s5, s5, 0
	s_add_u32 s6, s6, s28
	s_addc_u32 s7, s7, 0
	s_lshl_b32 s0, s26, 14
	s_lshl_b32 s27, s25, 4
	s_add_u32 s0, s0, s27
	s_add_u32 s18, s18, s0
	s_addc_u32 s19, s19, 0
	s_lshl_b32 s9, s9, 4
	s_mov_b64 s[12:13], s[6:7]
	s_mov_b32 m0, s9
	s_nop 0
	global_load_lds_dwordx4 v228, s[12:13]
	s_add_u32 s12, s12, 0x8000
	s_addc_u32 s13, s13, 0
	s_add_u32 m0, s9, 0x2000
	s_nop 0
	global_load_lds_dwordx4 v228, s[12:13]
	s_add_u32 s12, s12, 0x8000
	s_addc_u32 s13, s13, 0
	s_add_u32 m0, s9, 0x4000
	s_nop 0
	global_load_lds_dwordx4 v228, s[12:13]
	s_add_u32 s12, s12, 0x8000
	s_addc_u32 s13, s13, 0
	s_add_u32 m0, s9, 0x6000
	s_nop 0
	global_load_lds_dwordx4 v228, s[12:13]
	s_add_u32 s12, s12, 0x8000
	s_addc_u32 s13, s13, 0
	s_add_u32 m0, s9, 0x8000
	s_nop 0
	global_load_lds_dwordx4 v228, s[12:13]
	s_add_u32 s12, s12, 0x8000
	s_addc_u32 s13, s13, 0
	s_add_u32 m0, s9, 0xa000
	s_nop 0
	global_load_lds_dwordx4 v228, s[12:13]
	s_add_u32 s12, s12, 0x8000
	s_addc_u32 s13, s13, 0
	s_add_u32 m0, s9, 0xc000
	s_nop 0
	global_load_lds_dwordx4 v228, s[12:13]
	s_add_u32 s12, s12, 0x8000
	s_addc_u32 s13, s13, 0
	s_add_u32 m0, s9, 0xe000
	s_nop 0
	global_load_lds_dwordx4 v228, s[12:13]
	s_add_u32 s12, s12, 0x8000
	s_addc_u32 s13, s13, 0
	s_add_u32 m0, s9, 0x10000
	s_nop 0
	global_load_lds_dwordx4 v228, s[12:13]
	s_add_u32 s12, s12, 0x8000
	s_addc_u32 s13, s13, 0
	s_add_u32 m0, s9, 0x12000
	s_nop 0
	global_load_lds_dwordx4 v228, s[12:13]
	s_add_u32 s12, s12, 0x8000
	s_addc_u32 s13, s13, 0
	s_add_u32 m0, s9, 0x14000
	s_nop 0
	global_load_lds_dwordx4 v228, s[12:13]
	s_add_u32 s12, s12, 0x8000
	s_addc_u32 s13, s13, 0
	s_add_u32 m0, s9, 0x16000
	s_nop 0
	global_load_lds_dwordx4 v228, s[12:13]
	s_add_u32 s12, s12, 0x8000
	s_addc_u32 s13, s13, 0
	s_add_u32 m0, s9, 0x18000
	s_nop 0
	global_load_lds_dwordx4 v228, s[12:13]
	s_add_u32 s12, s12, 0x8000
	s_addc_u32 s13, s13, 0
	s_add_u32 m0, s9, 0x1a000
	s_nop 0
	global_load_lds_dwordx4 v228, s[12:13]
	s_add_u32 s12, s12, 0x8000
	s_addc_u32 s13, s13, 0
	s_add_u32 m0, s9, 0x1c000
	s_nop 0
	global_load_lds_dwordx4 v228, s[12:13]
	s_add_u32 s12, s12, 0x8000
	s_addc_u32 s13, s13, 0
	s_add_u32 m0, s9, 0x1e000
	s_nop 0
	global_load_lds_dwordx4 v228, s[12:13]
	v_add_u32_e32 v230, 0x2000, v227
	v_add_u32_e32 v231, 0x1000, v227
	v_add_u32_e32 v232, 0x34000, v227
	global_load_dwordx4 v[130:133], v230, s[10:11] offset:0
	global_load_dwordx4 v[134:137], v230, s[10:11] offset:64
	global_load_dwordx4 v[138:141], v230, s[10:11] offset:128
	global_load_dwordx4 v[142:145], v230, s[10:11] offset:192
	global_load_dwordx4 v[146:149], v227, s[4:5] offset:0
	global_load_dwordx4 v[150:153], v227, s[4:5] offset:64
	global_load_dwordx4 v[154:157], v227, s[4:5] offset:128
	global_load_dwordx4 v[158:161], v227, s[4:5] offset:192
	global_load_dwordx4 v[162:165], v231, s[10:11] offset:0
	global_load_dwordx4 v[166:169], v231, s[10:11] offset:64
	global_load_dwordx4 v[170:173], v231, s[10:11] offset:128
	global_load_dwordx4 v[174:177], v231, s[10:11] offset:192
	global_load_dwordx4 v[178:181], v231, s[4:5] offset:0
	global_load_dwordx4 v[182:185], v231, s[4:5] offset:64
	global_load_dwordx4 v[186:189], v231, s[4:5] offset:128
	global_load_dwordx4 v[190:193], v231, s[4:5] offset:192
	global_load_dwordx4 v[194:197], v232, s[10:11] offset:0
	global_load_dwordx4 v[198:201], v232, s[10:11] offset:64
	global_load_dwordx4 v[202:205], v232, s[10:11] offset:128
	global_load_dwordx4 v[206:209], v232, s[10:11] offset:192
	s_waitcnt vmcnt(20)
	s_barrier
; template <bool HN, bool L0>
; DI void phaseC_epi(const Params& p, f32x4 (&acc)[2][2][4][2], int l, int n0, int m0) {
;     ...
;     for (int ai = 0; ai < 2; ++ai)
; #pragma unroll
;       for (int g = 0; g < 4; ++g)
; #pragma unroll
;         for (int m = 0; m < 4; ++m)
; #pragma unroll
;           for (int j = 0; j < 4; ++j) acc[ai][g >> 1][m][g & 1][j] *= gt[ai][m][j];
;   }
;   __builtin_amdgcn_sched_barrier(0);
; #pragma unroll
;   for (int ai = 0; ai < 2; ++ai) {
;     const int f0 = n0 + ai * 128 + wr * 64 + fq * 4;
;     f32x4 gs[4], rgs[4];
; #pragma unroll
;     for (int m = 0; m < 4; ++m) {
;       if (!L0) {
;         const f32x4 g0 = *(const f32x4*)(p.norm_gain + (size_t)l * DM + f0 + m * 16);
;         const f32x4 s0 = *(const f32x4*)(p.mod + (size_t)(l * 17 + modrow) * 3072 + 1024 + f0 + m * 16);
; #pragma unroll
;         for (int j = 0; j < 4; ++j) rgs[m][j] = __builtin_amdgcn_rcpf(g0[j] * (1.f + s0[j]));
;       }
;       if (HN) {
;         const f32x4 g1 = *(const f32x4*)(p.norm_gain + (size_t)(l + 1) * DM + f0 + m * 16);
;         const f32x4 s1 = *(const f32x4*)(p.mod + (size_t)((l + 1) * 17 + modrow) * 3072 + 1024 + f0 + m * 16);
; #pragma unroll
;         for (int j = 0; j < 4; ++j) gs[m][j] = g1[j] * (1.f + s1[j]);
;       }
;     }
; #pragma unroll
;     for (int gp = 0; gp < 2; ++gp) {
;       f32x4 xv[2][4];
;       u32x2 xb[2][4];
; #pragma unroll
;       for (int n = 0; n < 2; ++n)
; #pragma unroll
;         for (int m = 0; m < 4; ++m) {
;           if (L0) xv[n][m] = *(const f32x4*)(xin0 + (size_t)(tok[gp * 2 + n] - rowoff) * DM + f0 + m * 16);
;           else xb[n][m] = *(const u32x2*)(p.xg + (size_t)tok[gp * 2 + n] * DM + f0 + m * 16);
;         }
; #pragma unroll
;       for (int n = 0; n < 2; ++n) {
;         const int g = gp * 2 + n;
;         float ss = 0.f;
; #pragma unroll
;         for (int m = 0; m < 4; ++m) {
;           f32x4 xx;
;           if (L0) xx = xv[n][m];
;           else {
;             xx[0] = hlo(xb[n][m][0]) * rgs[m][0]; xx[1] = hhi(xb[n][m][0]) * rgs[m][1];
;             xx[2] = hlo(xb[n][m][1]) * rgs[m][2]; xx[3] = hhi(xb[n][m][1]) * rgs[m][3];
;           }
;           f32x4 nv;
; #pragma unroll
;           for (int j = 0; j < 4; ++j) { nv[j] = xx[j] + acc[ai][gp][m][n][j]; ss += nv[j] * nv[j]; }
;           if (HN) {
;             u32x2 o;
;             o[0] = pkh2(nv[0] * gs[m][0], nv[1] * gs[m][1]);
	s_waitcnt vmcnt(0)
	v_add_f32_e32 v162, 1.0, v162
	v_add_f32_e32 v163, 1.0, v163
	v_pk_mul_f32 v[146:147], v[146:147], v[162:163]
	v_add_f32_e32 v194, 1.0, v194
	v_add_f32_e32 v195, 1.0, v195
	v_pk_mul_f32 v[178:179], v[178:179], v[194:195]
	v_add_f32_e32 v164, 1.0, v164
	v_add_f32_e32 v165, 1.0, v165
	v_pk_mul_f32 v[148:149], v[148:149], v[164:165]
	v_add_f32_e32 v196, 1.0, v196
	v_add_f32_e32 v197, 1.0, v197
	v_pk_mul_f32 v[180:181], v[180:181], v[196:197]
	v_add_f32_e32 v166, 1.0, v166
	v_add_f32_e32 v167, 1.0, v167
	v_pk_mul_f32 v[150:151], v[150:151], v[166:167]
	v_add_f32_e32 v198, 1.0, v198
	v_add_f32_e32 v199, 1.0, v199
	v_pk_mul_f32 v[182:183], v[182:183], v[198:199]
	v_add_f32_e32 v168, 1.0, v168
	v_add_f32_e32 v169, 1.0, v169
	v_pk_mul_f32 v[152:153], v[152:153], v[168:169]
	v_add_f32_e32 v200, 1.0, v200
	v_add_f32_e32 v201, 1.0, v201
	v_pk_mul_f32 v[184:185], v[184:185], v[200:201]
	v_add_f32_e32 v170, 1.0, v170
	v_add_f32_e32 v171, 1.0, v171
	v_pk_mul_f32 v[154:155], v[154:155], v[170:171]
	v_add_f32_e32 v202, 1.0, v202
	v_add_f32_e32 v203, 1.0, v203
	v_pk_mul_f32 v[186:187], v[186:187], v[202:203]
	v_add_f32_e32 v172, 1.0, v172
	v_add_f32_e32 v173, 1.0, v173
	v_pk_mul_f32 v[156:157], v[156:157], v[172:173]
	v_add_f32_e32 v204, 1.0, v204
	v_add_f32_e32 v205, 1.0, v205
	v_pk_mul_f32 v[188:189], v[188:189], v[204:205]
	v_add_f32_e32 v174, 1.0, v174
	v_add_f32_e32 v175, 1.0, v175
	v_pk_mul_f32 v[158:159], v[158:159], v[174:175]
	v_add_f32_e32 v206, 1.0, v206
	v_add_f32_e32 v207, 1.0, v207
	v_pk_mul_f32 v[190:191], v[190:191], v[206:207]
	v_add_f32_e32 v176, 1.0, v176
	v_add_f32_e32 v177, 1.0, v177
	v_pk_mul_f32 v[160:161], v[160:161], v[176:177]
	v_add_f32_e32 v208, 1.0, v208
	v_add_f32_e32 v209, 1.0, v209
	v_pk_mul_f32 v[192:193], v[192:193], v[208:209]
	v_rcp_f32_e32 v146, v146
	v_rcp_f32_e32 v147, v147
	v_rcp_f32_e32 v148, v148
	v_rcp_f32_e32 v149, v149
	v_rcp_f32_e32 v150, v150
	v_rcp_f32_e32 v151, v151
	v_rcp_f32_e32 v152, v152
	v_rcp_f32_e32 v153, v153
	v_rcp_f32_e32 v154, v154
	v_rcp_f32_e32 v155, v155
	v_rcp_f32_e32 v156, v156
	v_rcp_f32_e32 v157, v157
	v_rcp_f32_e32 v158, v158
	v_rcp_f32_e32 v159, v159
	v_rcp_f32_e32 v160, v160
	v_rcp_f32_e32 v161, v161
	v_pk_mul_f32 v[126:127], v[126:127], v[130:131]
	v_pk_mul_f32 v[128:129], v[128:129], v[132:133]
	v_pk_mul_f32 v[102:103], v[102:103], v[130:131]
	v_pk_mul_f32 v[104:105], v[104:105], v[132:133]
	v_pk_mul_f32 v[122:123], v[122:123], v[134:135]
	v_pk_mul_f32 v[124:125], v[124:125], v[136:137]
	v_pk_mul_f32 v[98:99], v[98:99], v[134:135]
	v_pk_mul_f32 v[100:101], v[100:101], v[136:137]
	v_pk_mul_f32 v[118:119], v[118:119], v[138:139]
	v_pk_mul_f32 v[120:121], v[120:121], v[140:141]
	v_pk_mul_f32 v[106:107], v[106:107], v[138:139]
	v_pk_mul_f32 v[108:109], v[108:109], v[140:141]
	v_pk_mul_f32 v[114:115], v[114:115], v[142:143]
	v_pk_mul_f32 v[116:117], v[116:117], v[144:145]
	v_pk_mul_f32 v[110:111], v[110:111], v[142:143]
	v_pk_mul_f32 v[112:113], v[112:113], v[144:145]
	v_pk_mul_f32 v[82:83], v[82:83], v[130:131]
	v_pk_mul_f32 v[84:85], v[84:85], v[132:133]
	v_pk_mul_f32 v[66:67], v[66:67], v[130:131]
	v_pk_mul_f32 v[68:69], v[68:69], v[132:133]
	v_pk_mul_f32 v[86:87], v[86:87], v[134:135]
	v_pk_mul_f32 v[88:89], v[88:89], v[136:137]
	v_pk_mul_f32 v[74:75], v[74:75], v[134:135]
	v_pk_mul_f32 v[76:77], v[76:77], v[136:137]
	v_pk_mul_f32 v[90:91], v[90:91], v[138:139]
	v_pk_mul_f32 v[92:93], v[92:93], v[140:141]
	v_pk_mul_f32 v[70:71], v[70:71], v[138:139]
	v_pk_mul_f32 v[72:73], v[72:73], v[140:141]
	v_pk_mul_f32 v[94:95], v[94:95], v[142:143]
	v_pk_mul_f32 v[96:97], v[96:97], v[144:145]
	v_pk_mul_f32 v[78:79], v[78:79], v[142:143]
	v_pk_mul_f32 v[80:81], v[80:81], v[144:145]
	v_bfe_u32 v0, v251, 6, 2
	v_and_b32_e32 v231, 15, v251
	v_lshl_or_b32 v0, v0, 5, v231
	v_lshlrev_b32_e32 v0, 9, v0
	v_bfe_u32 v232, v251, 4, 1
	v_lshl_or_b32 v0, v232, 3, v0
	v_bfe_u32 v232, v251, 5, 1
	v_bfe_u32 v233, v251, 8, 1
	v_lshl_or_b32 v232, v233, 3, v232
	v_xor_b32_e32 v232, v232, v231
	v_xor_b32_e32 v233, 0, v232
	v_lshl_or_b32 v166, v233, 4, v0
	v_xor_b32_e32 v233, 2, v232
	v_lshl_or_b32 v167, v233, 4, v0
	v_xor_b32_e32 v233, 4, v232
	v_lshl_or_b32 v168, v233, 4, v0
	v_xor_b32_e32 v233, 6, v232
	v_lshl_or_b32 v169, v233, 4, v0
	v_xor_b32_e32 v162, 16, v240
	v_lshlrev_b32_e32 v162, 2, v162
	v_xor_b32_e32 v163, 32, v240
	v_lshlrev_b32_e32 v163, 2, v163
	v_bfe_u32 v0, v251, 6, 2
	v_and_b32_e32 v164, 15, v251
	v_lshl_or_b32 v164, v0, 5, v164
	v_bfe_u32 v0, v251, 8, 1
	v_lshlrev_b32_e32 v164, 6, v164
	v_lshl_or_b32 v164, v0, 2, v164
	ds_read_b64 v[210:211], v166 offset:0
	ds_read_b64 v[212:213], v167 offset:0
	ds_read_b64 v[214:215], v168 offset:0
	ds_read_b64 v[216:217], v169 offset:0
	ds_read_b64 v[218:219], v166 offset:8192
	ds_read_b64 v[220:221], v167 offset:8192
	ds_read_b64 v[222:223], v168 offset:8192
	ds_read_b64 v[224:225], v169 offset:8192
	s_waitcnt lgkmcnt(7)
	v_cvt_f32_f16_e32 v230, v210
	v_cvt_f32_f16_sdwa v231, v210 dst_sel:DWORD dst_unused:UNUSED_PAD src0_sel:WORD_1
	v_cvt_f32_f16_e32 v232, v211
	v_cvt_f32_f16_sdwa v233, v211 dst_sel:DWORD dst_unused:UNUSED_PAD src0_sel:WORD_1
	v_pk_fma_f32 v[230:231], v[230:231], v[146:147], v[126:127]
	v_pk_fma_f32 v[232:233], v[232:233], v[148:149], v[128:129]
	v_pk_mul_f32 v[170:171], v[230:231], v[230:231]
	v_pk_fma_f32 v[170:171], v[232:233], v[232:233], v[170:171]
	v_pk_mul_f32 v[230:231], v[230:231], v[178:179]
	v_pk_mul_f32 v[232:233], v[232:233], v[180:181]
	v_cvt_pk_f16_f32 v210, v230, v231
	v_cvt_pk_f16_f32 v211, v232, v233
	ds_write_b64 v166, v[210:211] offset:0
	s_waitcnt lgkmcnt(7)
; DI float hlo(unsigned u) { const h2_t v = __builtin_bit_cast(h2_t, u); return (float)v[0]; }
; DI float hhi(unsigned u) { const h2_t v = __builtin_bit_cast(h2_t, u); return (float)v[1]; }
; template <bool HN, bool L0>
; DI void phaseC_epi(const Params& p, f32x4 (&acc)[2][2][4][2], int l, int n0, int m0) {
;     ...
;       for (int n = 0; n < 2; ++n) {
;         const int g = gp * 2 + n;
;         float ss = 0.f;
; #pragma unroll
;         for (int m = 0; m < 4; ++m) {
;           f32x4 xx;
;           if (L0) xx = xv[n][m];
;           else {
;             xx[0] = hlo(xb[n][m][0]) * rgs[m][0]; xx[1] = hhi(xb[n][m][0]) * rgs[m][1];
;             xx[2] = hlo(xb[n][m][1]) * rgs[m][2]; xx[3] = hhi(xb[n][m][1]) * rgs[m][3];
;           }
;           f32x4 nv;
; #pragma unroll
;           for (int j = 0; j < 4; ++j) { nv[j] = xx[j] + acc[ai][gp][m][n][j]; ss += nv[j] * nv[j]; }
;           if (HN) {
;             u32x2 o;
;             o[0] = pkh2(nv[0] * gs[m][0], nv[1] * gs[m][1]);
;             o[1] = pkh2(nv[2] * gs[m][2], nv[3] * gs[m][3]);
;             *(u32x2*)(p.xg + (size_t)tok[g] * DM + f0 + m * 16) = o;
;           } else {
;             *(f32x4*)(p.out + (size_t)tok[g] * DM + f0 + m * 16) = nv;
;           }
;         }
;         if (HN) {
;           ss += __shfl_xor(ss, 16);
;           ss += __shfl_xor(ss, 32);
;           if (fq == 0) p.ssq[(size_t)tok[g] * 16 + (n0 >> 6) + ai * 2 + wr] = ss;
;         }
	v_cvt_f32_f16_e32 v230, v212
	v_cvt_f32_f16_sdwa v231, v212 dst_sel:DWORD dst_unused:UNUSED_PAD src0_sel:WORD_1
	v_cvt_f32_f16_e32 v232, v213
	v_cvt_f32_f16_sdwa v233, v213 dst_sel:DWORD dst_unused:UNUSED_PAD src0_sel:WORD_1
	v_pk_fma_f32 v[230:231], v[230:231], v[150:151], v[122:123]
	v_pk_fma_f32 v[232:233], v[232:233], v[152:153], v[124:125]
	v_pk_fma_f32 v[170:171], v[230:231], v[230:231], v[170:171]
	v_pk_fma_f32 v[170:171], v[232:233], v[232:233], v[170:171]
	v_pk_mul_f32 v[230:231], v[230:231], v[182:183]
	v_pk_mul_f32 v[232:233], v[232:233], v[184:185]
	v_cvt_pk_f16_f32 v212, v230, v231
	v_cvt_pk_f16_f32 v213, v232, v233
	ds_write_b64 v167, v[212:213] offset:0
	s_waitcnt lgkmcnt(7)
	v_cvt_f32_f16_e32 v230, v214
	v_cvt_f32_f16_sdwa v231, v214 dst_sel:DWORD dst_unused:UNUSED_PAD src0_sel:WORD_1
	v_cvt_f32_f16_e32 v232, v215
	v_cvt_f32_f16_sdwa v233, v215 dst_sel:DWORD dst_unused:UNUSED_PAD src0_sel:WORD_1
	v_pk_fma_f32 v[230:231], v[230:231], v[154:155], v[118:119]
	v_pk_fma_f32 v[232:233], v[232:233], v[156:157], v[120:121]
	v_pk_fma_f32 v[170:171], v[230:231], v[230:231], v[170:171]
	v_pk_fma_f32 v[170:171], v[232:233], v[232:233], v[170:171]
	v_pk_mul_f32 v[230:231], v[230:231], v[186:187]
	v_pk_mul_f32 v[232:233], v[232:233], v[188:189]
	v_cvt_pk_f16_f32 v214, v230, v231
	v_cvt_pk_f16_f32 v215, v232, v233
	ds_write_b64 v168, v[214:215] offset:0
	s_waitcnt lgkmcnt(7)
	v_cvt_f32_f16_e32 v230, v216
	v_cvt_f32_f16_sdwa v231, v216 dst_sel:DWORD dst_unused:UNUSED_PAD src0_sel:WORD_1
	v_cvt_f32_f16_e32 v232, v217
	v_cvt_f32_f16_sdwa v233, v217 dst_sel:DWORD dst_unused:UNUSED_PAD src0_sel:WORD_1
	v_pk_fma_f32 v[230:231], v[230:231], v[158:159], v[114:115]
	v_pk_fma_f32 v[232:233], v[232:233], v[160:161], v[116:117]
	v_pk_fma_f32 v[170:171], v[230:231], v[230:231], v[170:171]
	v_pk_fma_f32 v[170:171], v[232:233], v[232:233], v[170:171]
	v_pk_mul_f32 v[230:231], v[230:231], v[190:191]
	v_pk_mul_f32 v[232:233], v[232:233], v[192:193]
	v_cvt_pk_f16_f32 v216, v230, v231
	v_cvt_pk_f16_f32 v217, v232, v233
	ds_write_b64 v169, v[216:217] offset:0
	s_waitcnt lgkmcnt(7)
	v_cvt_f32_f16_e32 v230, v218
	v_cvt_f32_f16_sdwa v231, v218 dst_sel:DWORD dst_unused:UNUSED_PAD src0_sel:WORD_1
	v_cvt_f32_f16_e32 v232, v219
	v_cvt_f32_f16_sdwa v233, v219 dst_sel:DWORD dst_unused:UNUSED_PAD src0_sel:WORD_1
	v_pk_fma_f32 v[230:231], v[230:231], v[146:147], v[102:103]
	v_pk_fma_f32 v[232:233], v[232:233], v[148:149], v[104:105]
	v_pk_mul_f32 v[172:173], v[230:231], v[230:231]
	v_pk_fma_f32 v[172:173], v[232:233], v[232:233], v[172:173]
	v_pk_mul_f32 v[230:231], v[230:231], v[178:179]
	v_pk_mul_f32 v[232:233], v[232:233], v[180:181]
	v_cvt_pk_f16_f32 v218, v230, v231
	v_cvt_pk_f16_f32 v219, v232, v233
	ds_write_b64 v166, v[218:219] offset:8192
	s_waitcnt lgkmcnt(7)
	v_cvt_f32_f16_e32 v230, v220
	v_cvt_f32_f16_sdwa v231, v220 dst_sel:DWORD dst_unused:UNUSED_PAD src0_sel:WORD_1
	v_cvt_f32_f16_e32 v232, v221
	v_cvt_f32_f16_sdwa v233, v221 dst_sel:DWORD dst_unused:UNUSED_PAD src0_sel:WORD_1
	v_pk_fma_f32 v[230:231], v[230:231], v[150:151], v[98:99]
	v_pk_fma_f32 v[232:233], v[232:233], v[152:153], v[100:101]
	v_pk_fma_f32 v[172:173], v[230:231], v[230:231], v[172:173]
	v_pk_fma_f32 v[172:173], v[232:233], v[232:233], v[172:173]
	v_pk_mul_f32 v[230:231], v[230:231], v[182:183]
	v_pk_mul_f32 v[232:233], v[232:233], v[184:185]
	v_cvt_pk_f16_f32 v220, v230, v231
	v_cvt_pk_f16_f32 v221, v232, v233
	ds_write_b64 v167, v[220:221] offset:8192
	s_waitcnt lgkmcnt(7)
	v_cvt_f32_f16_e32 v230, v222
	v_cvt_f32_f16_sdwa v231, v222 dst_sel:DWORD dst_unused:UNUSED_PAD src0_sel:WORD_1
	v_cvt_f32_f16_e32 v232, v223
	v_cvt_f32_f16_sdwa v233, v223 dst_sel:DWORD dst_unused:UNUSED_PAD src0_sel:WORD_1
	v_pk_fma_f32 v[230:231], v[230:231], v[154:155], v[106:107]
	v_pk_fma_f32 v[232:233], v[232:233], v[156:157], v[108:109]
	v_pk_fma_f32 v[172:173], v[230:231], v[230:231], v[172:173]
	v_pk_fma_f32 v[172:173], v[232:233], v[232:233], v[172:173]
	v_pk_mul_f32 v[230:231], v[230:231], v[186:187]
	v_pk_mul_f32 v[232:233], v[232:233], v[188:189]
	v_cvt_pk_f16_f32 v222, v230, v231
	v_cvt_pk_f16_f32 v223, v232, v233
	ds_write_b64 v168, v[222:223] offset:8192
	s_waitcnt lgkmcnt(7)
	v_cvt_f32_f16_e32 v230, v224
	v_cvt_f32_f16_sdwa v231, v224 dst_sel:DWORD dst_unused:UNUSED_PAD src0_sel:WORD_1
	v_cvt_f32_f16_e32 v232, v225
	v_cvt_f32_f16_sdwa v233, v225 dst_sel:DWORD dst_unused:UNUSED_PAD src0_sel:WORD_1
	v_pk_fma_f32 v[230:231], v[230:231], v[158:159], v[110:111]
	v_pk_fma_f32 v[232:233], v[232:233], v[160:161], v[112:113]
	v_pk_fma_f32 v[172:173], v[230:231], v[230:231], v[172:173]
	v_pk_fma_f32 v[172:173], v[232:233], v[232:233], v[172:173]
	v_pk_mul_f32 v[230:231], v[230:231], v[190:191]
	v_pk_mul_f32 v[232:233], v[232:233], v[192:193]
	v_cvt_pk_f16_f32 v224, v230, v231
	v_cvt_pk_f16_f32 v225, v232, v233
	ds_write_b64 v169, v[224:225] offset:8192
	v_add_f32_e32 v170, v170, v171
	v_add_f32_e32 v172, v172, v173
	ds_bpermute_b32 v171, v162, v170
	ds_bpermute_b32 v173, v162, v172
	s_waitcnt lgkmcnt(0)
	v_add_f32_e32 v170, v170, v171
	v_add_f32_e32 v172, v172, v173
	ds_bpermute_b32 v171, v163, v170
	ds_bpermute_b32 v173, v163, v172
	s_waitcnt lgkmcnt(0)
	v_add_f32_e32 v170, v170, v171
	v_add_f32_e32 v172, v172, v173
	s_mov_b64 exec, s[2:3]
	global_store_dword v164, v170, s[18:19] offset:0
	global_store_dword v164, v172, s[18:19] offset:1024
	s_mov_b64 exec, -1
	v_add_u32_e32 v166, 0x10000, v166
	v_add_u32_e32 v167, 0x10000, v167
	v_add_u32_e32 v168, 0x10000, v168
	v_add_u32_e32 v169, 0x10000, v169
	ds_read_b64 v[130:131], v166 offset:0
	ds_read_b64 v[132:133], v167 offset:0
	ds_read_b64 v[134:135], v168 offset:0
	ds_read_b64 v[136:137], v169 offset:0
	ds_read_b64 v[138:139], v166 offset:8192
	ds_read_b64 v[140:141], v167 offset:8192
	ds_read_b64 v[142:143], v168 offset:8192
	ds_read_b64 v[144:145], v169 offset:8192
	s_waitcnt lgkmcnt(7)
; DI float hlo(unsigned u) { const h2_t v = __builtin_bit_cast(h2_t, u); return (float)v[0]; }
; DI float hhi(unsigned u) { const h2_t v = __builtin_bit_cast(h2_t, u); return (float)v[1]; }
; template <bool HN, bool L0>
; DI void phaseC_epi(const Params& p, f32x4 (&acc)[2][2][4][2], int l, int n0, int m0) {
;     ...
;       for (int n = 0; n < 2; ++n) {
;         const int g = gp * 2 + n;
;         float ss = 0.f;
; #pragma unroll
;         for (int m = 0; m < 4; ++m) {
;           f32x4 xx;
;           if (L0) xx = xv[n][m];
;           else {
;             xx[0] = hlo(xb[n][m][0]) * rgs[m][0]; xx[1] = hhi(xb[n][m][0]) * rgs[m][1];
;             xx[2] = hlo(xb[n][m][1]) * rgs[m][2]; xx[3] = hhi(xb[n][m][1]) * rgs[m][3];
;           }
;           f32x4 nv;
; #pragma unroll
;           for (int j = 0; j < 4; ++j) { nv[j] = xx[j] + acc[ai][gp][m][n][j]; ss += nv[j] * nv[j]; }
;           if (HN) {
;             u32x2 o;
;             o[0] = pkh2(nv[0] * gs[m][0], nv[1] * gs[m][1]);
;             o[1] = pkh2(nv[2] * gs[m][2], nv[3] * gs[m][3]);
;             *(u32x2*)(p.xg + (size_t)tok[g] * DM + f0 + m * 16) = o;
;           } else {
;             *(f32x4*)(p.out + (size_t)tok[g] * DM + f0 + m * 16) = nv;
;           }
;         }
;         if (HN) {
;           ss += __shfl_xor(ss, 16);
;           ss += __shfl_xor(ss, 32);
;           if (fq == 0) p.ssq[(size_t)tok[g] * 16 + (n0 >> 6) + ai * 2 + wr] = ss;
;         }
	v_cvt_f32_f16_e32 v230, v130
	v_cvt_f32_f16_sdwa v231, v130 dst_sel:DWORD dst_unused:UNUSED_PAD src0_sel:WORD_1
	v_cvt_f32_f16_e32 v232, v131
	v_cvt_f32_f16_sdwa v233, v131 dst_sel:DWORD dst_unused:UNUSED_PAD src0_sel:WORD_1
	v_pk_fma_f32 v[230:231], v[230:231], v[146:147], v[82:83]
	v_pk_fma_f32 v[232:233], v[232:233], v[148:149], v[84:85]
	v_pk_mul_f32 v[174:175], v[230:231], v[230:231]
	v_pk_fma_f32 v[174:175], v[232:233], v[232:233], v[174:175]
	v_pk_mul_f32 v[230:231], v[230:231], v[178:179]
	v_pk_mul_f32 v[232:233], v[232:233], v[180:181]
	v_cvt_pk_f16_f32 v130, v230, v231
	v_cvt_pk_f16_f32 v131, v232, v233
	ds_write_b64 v166, v[130:131] offset:0
	s_waitcnt lgkmcnt(7)
	v_cvt_f32_f16_e32 v230, v132
	v_cvt_f32_f16_sdwa v231, v132 dst_sel:DWORD dst_unused:UNUSED_PAD src0_sel:WORD_1
	v_cvt_f32_f16_e32 v232, v133
	v_cvt_f32_f16_sdwa v233, v133 dst_sel:DWORD dst_unused:UNUSED_PAD src0_sel:WORD_1
	v_pk_fma_f32 v[230:231], v[230:231], v[150:151], v[86:87]
	v_pk_fma_f32 v[232:233], v[232:233], v[152:153], v[88:89]
	v_pk_fma_f32 v[174:175], v[230:231], v[230:231], v[174:175]
	v_pk_fma_f32 v[174:175], v[232:233], v[232:233], v[174:175]
	v_pk_mul_f32 v[230:231], v[230:231], v[182:183]
	v_pk_mul_f32 v[232:233], v[232:233], v[184:185]
	v_cvt_pk_f16_f32 v132, v230, v231
	v_cvt_pk_f16_f32 v133, v232, v233
	ds_write_b64 v167, v[132:133] offset:0
	s_waitcnt lgkmcnt(7)
	v_cvt_f32_f16_e32 v230, v134
	v_cvt_f32_f16_sdwa v231, v134 dst_sel:DWORD dst_unused:UNUSED_PAD src0_sel:WORD_1
	v_cvt_f32_f16_e32 v232, v135
	v_cvt_f32_f16_sdwa v233, v135 dst_sel:DWORD dst_unused:UNUSED_PAD src0_sel:WORD_1
	v_pk_fma_f32 v[230:231], v[230:231], v[154:155], v[90:91]
	v_pk_fma_f32 v[232:233], v[232:233], v[156:157], v[92:93]
	v_pk_fma_f32 v[174:175], v[230:231], v[230:231], v[174:175]
	v_pk_fma_f32 v[174:175], v[232:233], v[232:233], v[174:175]
	v_pk_mul_f32 v[230:231], v[230:231], v[186:187]
	v_pk_mul_f32 v[232:233], v[232:233], v[188:189]
	v_cvt_pk_f16_f32 v134, v230, v231
	v_cvt_pk_f16_f32 v135, v232, v233
	ds_write_b64 v168, v[134:135] offset:0
	s_waitcnt lgkmcnt(7)
	v_cvt_f32_f16_e32 v230, v136
	v_cvt_f32_f16_sdwa v231, v136 dst_sel:DWORD dst_unused:UNUSED_PAD src0_sel:WORD_1
	v_cvt_f32_f16_e32 v232, v137
	v_cvt_f32_f16_sdwa v233, v137 dst_sel:DWORD dst_unused:UNUSED_PAD src0_sel:WORD_1
	v_pk_fma_f32 v[230:231], v[230:231], v[158:159], v[94:95]
	v_pk_fma_f32 v[232:233], v[232:233], v[160:161], v[96:97]
	v_pk_fma_f32 v[174:175], v[230:231], v[230:231], v[174:175]
	v_pk_fma_f32 v[174:175], v[232:233], v[232:233], v[174:175]
	v_pk_mul_f32 v[230:231], v[230:231], v[190:191]
	v_pk_mul_f32 v[232:233], v[232:233], v[192:193]
	v_cvt_pk_f16_f32 v136, v230, v231
	v_cvt_pk_f16_f32 v137, v232, v233
	ds_write_b64 v169, v[136:137] offset:0
	s_waitcnt lgkmcnt(7)
	v_cvt_f32_f16_e32 v230, v138
	v_cvt_f32_f16_sdwa v231, v138 dst_sel:DWORD dst_unused:UNUSED_PAD src0_sel:WORD_1
	v_cvt_f32_f16_e32 v232, v139
	v_cvt_f32_f16_sdwa v233, v139 dst_sel:DWORD dst_unused:UNUSED_PAD src0_sel:WORD_1
	v_pk_fma_f32 v[230:231], v[230:231], v[146:147], v[66:67]
	v_pk_fma_f32 v[232:233], v[232:233], v[148:149], v[68:69]
	v_pk_mul_f32 v[176:177], v[230:231], v[230:231]
	v_pk_fma_f32 v[176:177], v[232:233], v[232:233], v[176:177]
	v_pk_mul_f32 v[230:231], v[230:231], v[178:179]
	v_pk_mul_f32 v[232:233], v[232:233], v[180:181]
	v_cvt_pk_f16_f32 v138, v230, v231
	v_cvt_pk_f16_f32 v139, v232, v233
	ds_write_b64 v166, v[138:139] offset:8192
	s_waitcnt lgkmcnt(7)
	v_cvt_f32_f16_e32 v230, v140
	v_cvt_f32_f16_sdwa v231, v140 dst_sel:DWORD dst_unused:UNUSED_PAD src0_sel:WORD_1
	v_cvt_f32_f16_e32 v232, v141
	v_cvt_f32_f16_sdwa v233, v141 dst_sel:DWORD dst_unused:UNUSED_PAD src0_sel:WORD_1
	v_pk_fma_f32 v[230:231], v[230:231], v[150:151], v[74:75]
	v_pk_fma_f32 v[232:233], v[232:233], v[152:153], v[76:77]
	v_pk_fma_f32 v[176:177], v[230:231], v[230:231], v[176:177]
	v_pk_fma_f32 v[176:177], v[232:233], v[232:233], v[176:177]
	v_pk_mul_f32 v[230:231], v[230:231], v[182:183]
	v_pk_mul_f32 v[232:233], v[232:233], v[184:185]
	v_cvt_pk_f16_f32 v140, v230, v231
	v_cvt_pk_f16_f32 v141, v232, v233
	ds_write_b64 v167, v[140:141] offset:8192
	s_waitcnt lgkmcnt(7)
	v_cvt_f32_f16_e32 v230, v142
	v_cvt_f32_f16_sdwa v231, v142 dst_sel:DWORD dst_unused:UNUSED_PAD src0_sel:WORD_1
	v_cvt_f32_f16_e32 v232, v143
	v_cvt_f32_f16_sdwa v233, v143 dst_sel:DWORD dst_unused:UNUSED_PAD src0_sel:WORD_1
	v_pk_fma_f32 v[230:231], v[230:231], v[154:155], v[70:71]
	v_pk_fma_f32 v[232:233], v[232:233], v[156:157], v[72:73]
	v_pk_fma_f32 v[176:177], v[230:231], v[230:231], v[176:177]
	v_pk_fma_f32 v[176:177], v[232:233], v[232:233], v[176:177]
	v_pk_mul_f32 v[230:231], v[230:231], v[186:187]
	v_pk_mul_f32 v[232:233], v[232:233], v[188:189]
	v_cvt_pk_f16_f32 v142, v230, v231
	v_cvt_pk_f16_f32 v143, v232, v233
	ds_write_b64 v168, v[142:143] offset:8192
	s_waitcnt lgkmcnt(7)
	v_cvt_f32_f16_e32 v230, v144
	v_cvt_f32_f16_sdwa v231, v144 dst_sel:DWORD dst_unused:UNUSED_PAD src0_sel:WORD_1
	v_cvt_f32_f16_e32 v232, v145
	v_cvt_f32_f16_sdwa v233, v145 dst_sel:DWORD dst_unused:UNUSED_PAD src0_sel:WORD_1
	v_pk_fma_f32 v[230:231], v[230:231], v[158:159], v[78:79]
	v_pk_fma_f32 v[232:233], v[232:233], v[160:161], v[80:81]
	v_pk_fma_f32 v[176:177], v[230:231], v[230:231], v[176:177]
	v_pk_fma_f32 v[176:177], v[232:233], v[232:233], v[176:177]
	v_pk_mul_f32 v[230:231], v[230:231], v[190:191]
	v_pk_mul_f32 v[232:233], v[232:233], v[192:193]
	v_cvt_pk_f16_f32 v144, v230, v231
	v_cvt_pk_f16_f32 v145, v232, v233
	ds_write_b64 v169, v[144:145] offset:8192
	v_add_f32_e32 v174, v174, v175
	v_add_f32_e32 v176, v176, v177
	ds_bpermute_b32 v175, v162, v174
	ds_bpermute_b32 v177, v162, v176
	s_waitcnt lgkmcnt(0)
; template <bool HN, bool L0>
; DI void phaseC_epi(const Params& p, f32x4 (&acc)[2][2][4][2], int l, int n0, int m0) {
;     ...
; #pragma unroll
;   for (int ai = 0; ai < 2; ++ai) {
;     const int f0 = n0 + ai * 128 + wr * 64 + fq * 4;
;     f32x4 gs[4], rgs[4];
; #pragma unroll
;     for (int m = 0; m < 4; ++m) {
;       if (!L0) {
;         const f32x4 g0 = *(const f32x4*)(p.norm_gain + (size_t)l * DM + f0 + m * 16);
;         const f32x4 s0 = *(const f32x4*)(p.mod + (size_t)(l * 17 + modrow) * 3072 + 1024 + f0 + m * 16);
; #pragma unroll
;         for (int j = 0; j < 4; ++j) rgs[m][j] = __builtin_amdgcn_rcpf(g0[j] * (1.f + s0[j]));
;       }
;       if (HN) {
;         const f32x4 g1 = *(const f32x4*)(p.norm_gain + (size_t)(l + 1) * DM + f0 + m * 16);
;         const f32x4 s1 = *(const f32x4*)(p.mod + (size_t)((l + 1) * 17 + modrow) * 3072 + 1024 + f0 + m * 16);
; #pragma unroll
;         for (int j = 0; j < 4; ++j) gs[m][j] = g1[j] * (1.f + s1[j]);
;       }
;     }
; #pragma unroll
;     for (int gp = 0; gp < 2; ++gp) {
;       f32x4 xv[2][4];
;       u32x2 xb[2][4];
; #pragma unroll
;       for (int n = 0; n < 2; ++n)
; #pragma unroll
;         for (int m = 0; m < 4; ++m) {
;           if (L0) xv[n][m] = *(const f32x4*)(xin0 + (size_t)(tok[gp * 2 + n] - rowoff) * DM + f0 + m * 16);
;           else xb[n][m] = *(const u32x2*)(p.xg + (size_t)tok[gp * 2 + n] * DM + f0 + m * 16);
;         }
; #pragma unroll
;       for (int n = 0; n < 2; ++n) {
;         const int g = gp * 2 + n;
;         float ss = 0.f;
; #pragma unroll
;         for (int m = 0; m < 4; ++m) {
;           f32x4 xx;
;           if (L0) xx = xv[n][m];
;           else {
;             xx[0] = hlo(xb[n][m][0]) * rgs[m][0]; xx[1] = hhi(xb[n][m][0]) * rgs[m][1];
;             xx[2] = hlo(xb[n][m][1]) * rgs[m][2]; xx[3] = hhi(xb[n][m][1]) * rgs[m][3];
;           }
;           f32x4 nv;
; #pragma unroll
;           for (int j = 0; j < 4; ++j) { nv[j] = xx[j] + acc[ai][gp][m][n][j]; ss += nv[j] * nv[j]; }
;           if (HN) {
;             u32x2 o;
;             o[0] = pkh2(nv[0] * gs[m][0], nv[1] * gs[m][1]);
;             o[1] = pkh2(nv[2] * gs[m][2], nv[3] * gs[m][3]);
;             *(u32x2*)(p.xg + (size_t)tok[g] * DM + f0 + m * 16) = o;
;           } else {
;             *(f32x4*)(p.out + (size_t)tok[g] * DM + f0 + m * 16) = nv;
;           }
;         }
;         if (HN) {
	v_add_f32_e32 v174, v174, v175
	v_add_f32_e32 v176, v176, v177
	ds_bpermute_b32 v175, v163, v174
	ds_bpermute_b32 v177, v163, v176
	s_waitcnt lgkmcnt(0)
	v_add_f32_e32 v174, v174, v175
	v_add_f32_e32 v176, v176, v177
	v_add_u32_e32 v229, 0x2000, v164
	s_mov_b64 exec, s[2:3]
	global_store_dword v229, v174, s[18:19] offset:0
	global_store_dword v229, v176, s[18:19] offset:1024
	s_mov_b64 exec, -1
	v_add_u32_e32 v230, 0x2000, v227
	v_add_u32_e32 v231, 0x1000, v227
	v_add_u32_e32 v232, 0x34000, v227
	global_load_dwordx4 v[130:133], v230, s[10:11] offset:512
	global_load_dwordx4 v[134:137], v230, s[10:11] offset:576
	global_load_dwordx4 v[138:141], v230, s[10:11] offset:640
	global_load_dwordx4 v[142:145], v230, s[10:11] offset:704
	global_load_dwordx4 v[146:149], v227, s[4:5] offset:512
	global_load_dwordx4 v[150:153], v227, s[4:5] offset:576
	global_load_dwordx4 v[154:157], v227, s[4:5] offset:640
	global_load_dwordx4 v[158:161], v227, s[4:5] offset:704
	global_load_dwordx4 v[162:165], v231, s[10:11] offset:512
	global_load_dwordx4 v[166:169], v231, s[10:11] offset:576
	global_load_dwordx4 v[170:173], v231, s[10:11] offset:640
	global_load_dwordx4 v[174:177], v231, s[10:11] offset:704
	global_load_dwordx4 v[178:181], v231, s[4:5] offset:512
	global_load_dwordx4 v[182:185], v231, s[4:5] offset:576
	global_load_dwordx4 v[186:189], v231, s[4:5] offset:640
	global_load_dwordx4 v[190:193], v231, s[4:5] offset:704
	global_load_dwordx4 v[194:197], v232, s[10:11] offset:512
	global_load_dwordx4 v[198:201], v232, s[10:11] offset:576
	global_load_dwordx4 v[202:205], v232, s[10:11] offset:640
	global_load_dwordx4 v[206:209], v232, s[10:11] offset:704
	s_waitcnt vmcnt(0)
	v_add_f32_e32 v162, 1.0, v162
	v_add_f32_e32 v163, 1.0, v163
	v_pk_mul_f32 v[146:147], v[146:147], v[162:163]
	v_add_f32_e32 v194, 1.0, v194
	v_add_f32_e32 v195, 1.0, v195
	v_pk_mul_f32 v[178:179], v[178:179], v[194:195]
	v_add_f32_e32 v164, 1.0, v164
	v_add_f32_e32 v165, 1.0, v165
	v_pk_mul_f32 v[148:149], v[148:149], v[164:165]
	v_add_f32_e32 v196, 1.0, v196
	v_add_f32_e32 v197, 1.0, v197
	v_pk_mul_f32 v[180:181], v[180:181], v[196:197]
	v_add_f32_e32 v166, 1.0, v166
	v_add_f32_e32 v167, 1.0, v167
	v_pk_mul_f32 v[150:151], v[150:151], v[166:167]
	v_add_f32_e32 v198, 1.0, v198
	v_add_f32_e32 v199, 1.0, v199
	v_pk_mul_f32 v[182:183], v[182:183], v[198:199]
	v_add_f32_e32 v168, 1.0, v168
	v_add_f32_e32 v169, 1.0, v169
	v_pk_mul_f32 v[152:153], v[152:153], v[168:169]
	v_add_f32_e32 v200, 1.0, v200
	v_add_f32_e32 v201, 1.0, v201
	v_pk_mul_f32 v[184:185], v[184:185], v[200:201]
	v_add_f32_e32 v170, 1.0, v170
	v_add_f32_e32 v171, 1.0, v171
	v_pk_mul_f32 v[154:155], v[154:155], v[170:171]
	v_add_f32_e32 v202, 1.0, v202
	v_add_f32_e32 v203, 1.0, v203
	v_pk_mul_f32 v[186:187], v[186:187], v[202:203]
	v_add_f32_e32 v172, 1.0, v172
	v_add_f32_e32 v173, 1.0, v173
	v_pk_mul_f32 v[156:157], v[156:157], v[172:173]
	v_add_f32_e32 v204, 1.0, v204
	v_add_f32_e32 v205, 1.0, v205
	v_pk_mul_f32 v[188:189], v[188:189], v[204:205]
	v_add_f32_e32 v174, 1.0, v174
	v_add_f32_e32 v175, 1.0, v175
	v_pk_mul_f32 v[158:159], v[158:159], v[174:175]
	v_add_f32_e32 v206, 1.0, v206
	v_add_f32_e32 v207, 1.0, v207
	v_pk_mul_f32 v[190:191], v[190:191], v[206:207]
	v_add_f32_e32 v176, 1.0, v176
	v_add_f32_e32 v177, 1.0, v177
	v_pk_mul_f32 v[160:161], v[160:161], v[176:177]
	v_add_f32_e32 v208, 1.0, v208
	v_add_f32_e32 v209, 1.0, v209
	v_pk_mul_f32 v[192:193], v[192:193], v[208:209]
	v_rcp_f32_e32 v146, v146
	v_rcp_f32_e32 v147, v147
	v_rcp_f32_e32 v148, v148
	v_rcp_f32_e32 v149, v149
	v_rcp_f32_e32 v150, v150
	v_rcp_f32_e32 v151, v151
	v_rcp_f32_e32 v152, v152
	v_rcp_f32_e32 v153, v153
	v_rcp_f32_e32 v154, v154
	v_rcp_f32_e32 v155, v155
	v_rcp_f32_e32 v156, v156
	v_rcp_f32_e32 v157, v157
	v_rcp_f32_e32 v158, v158
	v_rcp_f32_e32 v159, v159
	v_rcp_f32_e32 v160, v160
	v_rcp_f32_e32 v161, v161
	v_pk_mul_f32 v[50:51], v[50:51], v[130:131]
	v_pk_mul_f32 v[52:53], v[52:53], v[132:133]
	v_pk_mul_f32 v[34:35], v[34:35], v[130:131]
	v_pk_mul_f32 v[36:37], v[36:37], v[132:133]
	v_pk_mul_f32 v[54:55], v[54:55], v[134:135]
	v_pk_mul_f32 v[56:57], v[56:57], v[136:137]
	v_pk_mul_f32 v[38:39], v[38:39], v[134:135]
	v_pk_mul_f32 v[40:41], v[40:41], v[136:137]
	v_pk_mul_f32 v[58:59], v[58:59], v[138:139]
	v_pk_mul_f32 v[60:61], v[60:61], v[140:141]
	v_pk_mul_f32 v[42:43], v[42:43], v[138:139]
	v_pk_mul_f32 v[44:45], v[44:45], v[140:141]
	v_pk_mul_f32 v[62:63], v[62:63], v[142:143]
	v_pk_mul_f32 v[64:65], v[64:65], v[144:145]
	v_pk_mul_f32 v[46:47], v[46:47], v[142:143]
	v_pk_mul_f32 v[48:49], v[48:49], v[144:145]
	v_pk_mul_f32 v[18:19], v[18:19], v[130:131]
	v_pk_mul_f32 v[20:21], v[20:21], v[132:133]
	v_pk_mul_f32 v[2:3], v[2:3], v[130:131]
	v_pk_mul_f32 v[4:5], v[4:5], v[132:133]
	v_pk_mul_f32 v[22:23], v[22:23], v[134:135]
	v_pk_mul_f32 v[24:25], v[24:25], v[136:137]
	v_pk_mul_f32 v[10:11], v[10:11], v[134:135]
	v_pk_mul_f32 v[12:13], v[12:13], v[136:137]
	v_pk_mul_f32 v[26:27], v[26:27], v[138:139]
	v_pk_mul_f32 v[28:29], v[28:29], v[140:141]
	v_pk_mul_f32 v[6:7], v[6:7], v[138:139]
	v_pk_mul_f32 v[8:9], v[8:9], v[140:141]
	v_pk_mul_f32 v[30:31], v[30:31], v[142:143]
	v_pk_mul_f32 v[32:33], v[32:33], v[144:145]
	v_pk_mul_f32 v[14:15], v[14:15], v[142:143]
	v_pk_mul_f32 v[16:17], v[16:17], v[144:145]
	v_bfe_u32 v0, v251, 6, 2
	v_and_b32_e32 v231, 15, v251
	v_lshl_or_b32 v0, v0, 5, v231
	v_lshlrev_b32_e32 v0, 9, v0
	v_bfe_u32 v232, v251, 4, 1
	v_lshl_or_b32 v0, v232, 3, v0
	v_bfe_u32 v232, v251, 5, 1
	v_bfe_u32 v233, v251, 8, 1
	v_lshl_or_b32 v232, v233, 3, v232
	v_xor_b32_e32 v232, v232, v231
	v_xor_b32_e32 v233, 0, v232
	v_lshl_or_b32 v166, v233, 4, v0
	v_xor_b32_e32 v233, 2, v232
	v_lshl_or_b32 v167, v233, 4, v0
	v_xor_b32_e32 v233, 4, v232
	v_lshl_or_b32 v168, v233, 4, v0
	v_xor_b32_e32 v233, 6, v232
	v_lshl_or_b32 v169, v233, 4, v0
	v_xor_b32_e32 v162, 16, v240
	v_lshlrev_b32_e32 v162, 2, v162
	v_xor_b32_e32 v163, 32, v240
	v_lshlrev_b32_e32 v163, 2, v163
	v_bfe_u32 v0, v251, 6, 2
	v_and_b32_e32 v164, 15, v251
	v_lshl_or_b32 v164, v0, 5, v164
	v_bfe_u32 v0, v251, 8, 1
	v_lshlrev_b32_e32 v164, 6, v164
	v_lshl_or_b32 v164, v0, 2, v164
	ds_read_b64 v[210:211], v166 offset:256
	ds_read_b64 v[212:213], v167 offset:256
	ds_read_b64 v[214:215], v168 offset:256
	ds_read_b64 v[216:217], v169 offset:256
	ds_read_b64 v[218:219], v166 offset:8448
	ds_read_b64 v[220:221], v167 offset:8448
	ds_read_b64 v[222:223], v168 offset:8448
	ds_read_b64 v[224:225], v169 offset:8448
	s_waitcnt lgkmcnt(7)
; DI float hlo(unsigned u) { const h2_t v = __builtin_bit_cast(h2_t, u); return (float)v[0]; }
; DI float hhi(unsigned u) { const h2_t v = __builtin_bit_cast(h2_t, u); return (float)v[1]; }
; template <bool HN, bool L0>
; DI void phaseC_epi(const Params& p, f32x4 (&acc)[2][2][4][2], int l, int n0, int m0) {
;     ...
;       for (int n = 0; n < 2; ++n) {
;         const int g = gp * 2 + n;
;         float ss = 0.f;
; #pragma unroll
;         for (int m = 0; m < 4; ++m) {
;           f32x4 xx;
;           if (L0) xx = xv[n][m];
;           else {
;             xx[0] = hlo(xb[n][m][0]) * rgs[m][0]; xx[1] = hhi(xb[n][m][0]) * rgs[m][1];
;             xx[2] = hlo(xb[n][m][1]) * rgs[m][2]; xx[3] = hhi(xb[n][m][1]) * rgs[m][3];
;           }
;           f32x4 nv;
; #pragma unroll
;           for (int j = 0; j < 4; ++j) { nv[j] = xx[j] + acc[ai][gp][m][n][j]; ss += nv[j] * nv[j]; }
;           if (HN) {
;             u32x2 o;
;             o[0] = pkh2(nv[0] * gs[m][0], nv[1] * gs[m][1]);
;             o[1] = pkh2(nv[2] * gs[m][2], nv[3] * gs[m][3]);
;             *(u32x2*)(p.xg + (size_t)tok[g] * DM + f0 + m * 16) = o;
;           } else {
;             *(f32x4*)(p.out + (size_t)tok[g] * DM + f0 + m * 16) = nv;
;           }
;         }
;         if (HN) {
;           ss += __shfl_xor(ss, 16);
;           ss += __shfl_xor(ss, 32);
;           if (fq == 0) p.ssq[(size_t)tok[g] * 16 + (n0 >> 6) + ai * 2 + wr] = ss;
;         }
	v_cvt_f32_f16_e32 v230, v210
	v_cvt_f32_f16_sdwa v231, v210 dst_sel:DWORD dst_unused:UNUSED_PAD src0_sel:WORD_1
	v_cvt_f32_f16_e32 v232, v211
	v_cvt_f32_f16_sdwa v233, v211 dst_sel:DWORD dst_unused:UNUSED_PAD src0_sel:WORD_1
	v_pk_fma_f32 v[230:231], v[230:231], v[146:147], v[50:51]
	v_pk_fma_f32 v[232:233], v[232:233], v[148:149], v[52:53]
	v_pk_mul_f32 v[170:171], v[230:231], v[230:231]
	v_pk_fma_f32 v[170:171], v[232:233], v[232:233], v[170:171]
	v_pk_mul_f32 v[230:231], v[230:231], v[178:179]
	v_pk_mul_f32 v[232:233], v[232:233], v[180:181]
	v_cvt_pk_f16_f32 v210, v230, v231
	v_cvt_pk_f16_f32 v211, v232, v233
	ds_write_b64 v166, v[210:211] offset:256
	s_waitcnt lgkmcnt(7)
	v_cvt_f32_f16_e32 v230, v212
	v_cvt_f32_f16_sdwa v231, v212 dst_sel:DWORD dst_unused:UNUSED_PAD src0_sel:WORD_1
	v_cvt_f32_f16_e32 v232, v213
	v_cvt_f32_f16_sdwa v233, v213 dst_sel:DWORD dst_unused:UNUSED_PAD src0_sel:WORD_1
	v_pk_fma_f32 v[230:231], v[230:231], v[150:151], v[54:55]
	v_pk_fma_f32 v[232:233], v[232:233], v[152:153], v[56:57]
	v_pk_fma_f32 v[170:171], v[230:231], v[230:231], v[170:171]
	v_pk_fma_f32 v[170:171], v[232:233], v[232:233], v[170:171]
	v_pk_mul_f32 v[230:231], v[230:231], v[182:183]
	v_pk_mul_f32 v[232:233], v[232:233], v[184:185]
	v_cvt_pk_f16_f32 v212, v230, v231
	v_cvt_pk_f16_f32 v213, v232, v233
	ds_write_b64 v167, v[212:213] offset:256
	s_waitcnt lgkmcnt(7)
	v_cvt_f32_f16_e32 v230, v214
	v_cvt_f32_f16_sdwa v231, v214 dst_sel:DWORD dst_unused:UNUSED_PAD src0_sel:WORD_1
	v_cvt_f32_f16_e32 v232, v215
	v_cvt_f32_f16_sdwa v233, v215 dst_sel:DWORD dst_unused:UNUSED_PAD src0_sel:WORD_1
	v_pk_fma_f32 v[230:231], v[230:231], v[154:155], v[58:59]
	v_pk_fma_f32 v[232:233], v[232:233], v[156:157], v[60:61]
	v_pk_fma_f32 v[170:171], v[230:231], v[230:231], v[170:171]
	v_pk_fma_f32 v[170:171], v[232:233], v[232:233], v[170:171]
	v_pk_mul_f32 v[230:231], v[230:231], v[186:187]
	v_pk_mul_f32 v[232:233], v[232:233], v[188:189]
	v_cvt_pk_f16_f32 v214, v230, v231
	v_cvt_pk_f16_f32 v215, v232, v233
	ds_write_b64 v168, v[214:215] offset:256
	s_waitcnt lgkmcnt(7)
	v_cvt_f32_f16_e32 v230, v216
	v_cvt_f32_f16_sdwa v231, v216 dst_sel:DWORD dst_unused:UNUSED_PAD src0_sel:WORD_1
	v_cvt_f32_f16_e32 v232, v217
	v_cvt_f32_f16_sdwa v233, v217 dst_sel:DWORD dst_unused:UNUSED_PAD src0_sel:WORD_1
	v_pk_fma_f32 v[230:231], v[230:231], v[158:159], v[62:63]
	v_pk_fma_f32 v[232:233], v[232:233], v[160:161], v[64:65]
	v_pk_fma_f32 v[170:171], v[230:231], v[230:231], v[170:171]
	v_pk_fma_f32 v[170:171], v[232:233], v[232:233], v[170:171]
	v_pk_mul_f32 v[230:231], v[230:231], v[190:191]
	v_pk_mul_f32 v[232:233], v[232:233], v[192:193]
	v_cvt_pk_f16_f32 v216, v230, v231
	v_cvt_pk_f16_f32 v217, v232, v233
	ds_write_b64 v169, v[216:217] offset:256
	s_waitcnt lgkmcnt(7)
	v_cvt_f32_f16_e32 v230, v218
	v_cvt_f32_f16_sdwa v231, v218 dst_sel:DWORD dst_unused:UNUSED_PAD src0_sel:WORD_1
	v_cvt_f32_f16_e32 v232, v219
	v_cvt_f32_f16_sdwa v233, v219 dst_sel:DWORD dst_unused:UNUSED_PAD src0_sel:WORD_1
	v_pk_fma_f32 v[230:231], v[230:231], v[146:147], v[34:35]
	v_pk_fma_f32 v[232:233], v[232:233], v[148:149], v[36:37]
	v_pk_mul_f32 v[172:173], v[230:231], v[230:231]
	v_pk_fma_f32 v[172:173], v[232:233], v[232:233], v[172:173]
	v_pk_mul_f32 v[230:231], v[230:231], v[178:179]
	v_pk_mul_f32 v[232:233], v[232:233], v[180:181]
	v_cvt_pk_f16_f32 v218, v230, v231
	v_cvt_pk_f16_f32 v219, v232, v233
	ds_write_b64 v166, v[218:219] offset:8448
	s_waitcnt lgkmcnt(7)
	v_cvt_f32_f16_e32 v230, v220
	v_cvt_f32_f16_sdwa v231, v220 dst_sel:DWORD dst_unused:UNUSED_PAD src0_sel:WORD_1
	v_cvt_f32_f16_e32 v232, v221
	v_cvt_f32_f16_sdwa v233, v221 dst_sel:DWORD dst_unused:UNUSED_PAD src0_sel:WORD_1
	v_pk_fma_f32 v[230:231], v[230:231], v[150:151], v[38:39]
	v_pk_fma_f32 v[232:233], v[232:233], v[152:153], v[40:41]
	v_pk_fma_f32 v[172:173], v[230:231], v[230:231], v[172:173]
	v_pk_fma_f32 v[172:173], v[232:233], v[232:233], v[172:173]
	v_pk_mul_f32 v[230:231], v[230:231], v[182:183]
	v_pk_mul_f32 v[232:233], v[232:233], v[184:185]
	v_cvt_pk_f16_f32 v220, v230, v231
	v_cvt_pk_f16_f32 v221, v232, v233
	ds_write_b64 v167, v[220:221] offset:8448
	s_waitcnt lgkmcnt(7)
	v_cvt_f32_f16_e32 v230, v222
	v_cvt_f32_f16_sdwa v231, v222 dst_sel:DWORD dst_unused:UNUSED_PAD src0_sel:WORD_1
	v_cvt_f32_f16_e32 v232, v223
	v_cvt_f32_f16_sdwa v233, v223 dst_sel:DWORD dst_unused:UNUSED_PAD src0_sel:WORD_1
	v_pk_fma_f32 v[230:231], v[230:231], v[154:155], v[42:43]
	v_pk_fma_f32 v[232:233], v[232:233], v[156:157], v[44:45]
	v_pk_fma_f32 v[172:173], v[230:231], v[230:231], v[172:173]
	v_pk_fma_f32 v[172:173], v[232:233], v[232:233], v[172:173]
	v_pk_mul_f32 v[230:231], v[230:231], v[186:187]
	v_pk_mul_f32 v[232:233], v[232:233], v[188:189]
	v_cvt_pk_f16_f32 v222, v230, v231
	v_cvt_pk_f16_f32 v223, v232, v233
	ds_write_b64 v168, v[222:223] offset:8448
	s_waitcnt lgkmcnt(7)
	v_cvt_f32_f16_e32 v230, v224
	v_cvt_f32_f16_sdwa v231, v224 dst_sel:DWORD dst_unused:UNUSED_PAD src0_sel:WORD_1
	v_cvt_f32_f16_e32 v232, v225
	v_cvt_f32_f16_sdwa v233, v225 dst_sel:DWORD dst_unused:UNUSED_PAD src0_sel:WORD_1
	v_pk_fma_f32 v[230:231], v[230:231], v[158:159], v[46:47]
	v_pk_fma_f32 v[232:233], v[232:233], v[160:161], v[48:49]
	v_pk_fma_f32 v[172:173], v[230:231], v[230:231], v[172:173]
	v_pk_fma_f32 v[172:173], v[232:233], v[232:233], v[172:173]
	v_pk_mul_f32 v[230:231], v[230:231], v[190:191]
	v_pk_mul_f32 v[232:233], v[232:233], v[192:193]
	v_cvt_pk_f16_f32 v224, v230, v231
	v_cvt_pk_f16_f32 v225, v232, v233
	ds_write_b64 v169, v[224:225] offset:8448
	v_add_f32_e32 v170, v170, v171
	v_add_f32_e32 v172, v172, v173
	ds_bpermute_b32 v171, v162, v170
	ds_bpermute_b32 v173, v162, v172
	s_waitcnt lgkmcnt(0)
; DI float hlo(unsigned u) { const h2_t v = __builtin_bit_cast(h2_t, u); return (float)v[0]; }
; DI float hhi(unsigned u) { const h2_t v = __builtin_bit_cast(h2_t, u); return (float)v[1]; }
; template <bool HN, bool L0>
; DI void phaseC_epi(const Params& p, f32x4 (&acc)[2][2][4][2], int l, int n0, int m0) {
;     ...
;       for (int n = 0; n < 2; ++n) {
;         const int g = gp * 2 + n;
;         float ss = 0.f;
; #pragma unroll
;         for (int m = 0; m < 4; ++m) {
;           f32x4 xx;
;           if (L0) xx = xv[n][m];
;           else {
;             xx[0] = hlo(xb[n][m][0]) * rgs[m][0]; xx[1] = hhi(xb[n][m][0]) * rgs[m][1];
;             xx[2] = hlo(xb[n][m][1]) * rgs[m][2]; xx[3] = hhi(xb[n][m][1]) * rgs[m][3];
;           }
;           f32x4 nv;
; #pragma unroll
;           for (int j = 0; j < 4; ++j) { nv[j] = xx[j] + acc[ai][gp][m][n][j]; ss += nv[j] * nv[j]; }
;           if (HN) {
;             u32x2 o;
;             o[0] = pkh2(nv[0] * gs[m][0], nv[1] * gs[m][1]);
;             o[1] = pkh2(nv[2] * gs[m][2], nv[3] * gs[m][3]);
;             *(u32x2*)(p.xg + (size_t)tok[g] * DM + f0 + m * 16) = o;
;           } else {
;             *(f32x4*)(p.out + (size_t)tok[g] * DM + f0 + m * 16) = nv;
;           }
;         }
;         if (HN) {
;           ss += __shfl_xor(ss, 16);
;           ss += __shfl_xor(ss, 32);
;           if (fq == 0) p.ssq[(size_t)tok[g] * 16 + (n0 >> 6) + ai * 2 + wr] = ss;
;         }
	v_add_f32_e32 v170, v170, v171
	v_add_f32_e32 v172, v172, v173
	ds_bpermute_b32 v171, v163, v170
	ds_bpermute_b32 v173, v163, v172
	s_waitcnt lgkmcnt(0)
	v_add_f32_e32 v170, v170, v171
	v_add_f32_e32 v172, v172, v173
	s_mov_b64 exec, s[2:3]
	global_store_dword v164, v170, s[18:19] offset:8
	global_store_dword v164, v172, s[18:19] offset:1032
	s_mov_b64 exec, -1
	v_add_u32_e32 v166, 0x10000, v166
	v_add_u32_e32 v167, 0x10000, v167
	v_add_u32_e32 v168, 0x10000, v168
	v_add_u32_e32 v169, 0x10000, v169
	ds_read_b64 v[130:131], v166 offset:256
	ds_read_b64 v[132:133], v167 offset:256
	ds_read_b64 v[134:135], v168 offset:256
	ds_read_b64 v[136:137], v169 offset:256
	ds_read_b64 v[138:139], v166 offset:8448
	ds_read_b64 v[140:141], v167 offset:8448
	ds_read_b64 v[142:143], v168 offset:8448
	ds_read_b64 v[144:145], v169 offset:8448
	s_waitcnt lgkmcnt(7)
	v_cvt_f32_f16_e32 v230, v130
	v_cvt_f32_f16_sdwa v231, v130 dst_sel:DWORD dst_unused:UNUSED_PAD src0_sel:WORD_1
	v_cvt_f32_f16_e32 v232, v131
	v_cvt_f32_f16_sdwa v233, v131 dst_sel:DWORD dst_unused:UNUSED_PAD src0_sel:WORD_1
	v_pk_fma_f32 v[230:231], v[230:231], v[146:147], v[18:19]
	v_pk_fma_f32 v[232:233], v[232:233], v[148:149], v[20:21]
	v_pk_mul_f32 v[174:175], v[230:231], v[230:231]
	v_pk_fma_f32 v[174:175], v[232:233], v[232:233], v[174:175]
	v_pk_mul_f32 v[230:231], v[230:231], v[178:179]
	v_pk_mul_f32 v[232:233], v[232:233], v[180:181]
	v_cvt_pk_f16_f32 v130, v230, v231
	v_cvt_pk_f16_f32 v131, v232, v233
	ds_write_b64 v166, v[130:131] offset:256
	s_waitcnt lgkmcnt(7)
	v_cvt_f32_f16_e32 v230, v132
	v_cvt_f32_f16_sdwa v231, v132 dst_sel:DWORD dst_unused:UNUSED_PAD src0_sel:WORD_1
	v_cvt_f32_f16_e32 v232, v133
	v_cvt_f32_f16_sdwa v233, v133 dst_sel:DWORD dst_unused:UNUSED_PAD src0_sel:WORD_1
	v_pk_fma_f32 v[230:231], v[230:231], v[150:151], v[22:23]
	v_pk_fma_f32 v[232:233], v[232:233], v[152:153], v[24:25]
	v_pk_fma_f32 v[174:175], v[230:231], v[230:231], v[174:175]
	v_pk_fma_f32 v[174:175], v[232:233], v[232:233], v[174:175]
	v_pk_mul_f32 v[230:231], v[230:231], v[182:183]
	v_pk_mul_f32 v[232:233], v[232:233], v[184:185]
	v_cvt_pk_f16_f32 v132, v230, v231
	v_cvt_pk_f16_f32 v133, v232, v233
	ds_write_b64 v167, v[132:133] offset:256
	s_waitcnt lgkmcnt(7)
	v_cvt_f32_f16_e32 v230, v134
	v_cvt_f32_f16_sdwa v231, v134 dst_sel:DWORD dst_unused:UNUSED_PAD src0_sel:WORD_1
	v_cvt_f32_f16_e32 v232, v135
	v_cvt_f32_f16_sdwa v233, v135 dst_sel:DWORD dst_unused:UNUSED_PAD src0_sel:WORD_1
	v_pk_fma_f32 v[230:231], v[230:231], v[154:155], v[26:27]
	v_pk_fma_f32 v[232:233], v[232:233], v[156:157], v[28:29]
	v_pk_fma_f32 v[174:175], v[230:231], v[230:231], v[174:175]
	v_pk_fma_f32 v[174:175], v[232:233], v[232:233], v[174:175]
	v_pk_mul_f32 v[230:231], v[230:231], v[186:187]
	v_pk_mul_f32 v[232:233], v[232:233], v[188:189]
	v_cvt_pk_f16_f32 v134, v230, v231
	v_cvt_pk_f16_f32 v135, v232, v233
	ds_write_b64 v168, v[134:135] offset:256
	s_waitcnt lgkmcnt(7)
	v_cvt_f32_f16_e32 v230, v136
	v_cvt_f32_f16_sdwa v231, v136 dst_sel:DWORD dst_unused:UNUSED_PAD src0_sel:WORD_1
	v_cvt_f32_f16_e32 v232, v137
	v_cvt_f32_f16_sdwa v233, v137 dst_sel:DWORD dst_unused:UNUSED_PAD src0_sel:WORD_1
	v_pk_fma_f32 v[230:231], v[230:231], v[158:159], v[30:31]
	v_pk_fma_f32 v[232:233], v[232:233], v[160:161], v[32:33]
	v_pk_fma_f32 v[174:175], v[230:231], v[230:231], v[174:175]
	v_pk_fma_f32 v[174:175], v[232:233], v[232:233], v[174:175]
	v_pk_mul_f32 v[230:231], v[230:231], v[190:191]
	v_pk_mul_f32 v[232:233], v[232:233], v[192:193]
	v_cvt_pk_f16_f32 v136, v230, v231
	v_cvt_pk_f16_f32 v137, v232, v233
	ds_write_b64 v169, v[136:137] offset:256
	s_waitcnt lgkmcnt(7)
	v_cvt_f32_f16_e32 v230, v138
	v_cvt_f32_f16_sdwa v231, v138 dst_sel:DWORD dst_unused:UNUSED_PAD src0_sel:WORD_1
	v_cvt_f32_f16_e32 v232, v139
	v_cvt_f32_f16_sdwa v233, v139 dst_sel:DWORD dst_unused:UNUSED_PAD src0_sel:WORD_1
	v_pk_fma_f32 v[230:231], v[230:231], v[146:147], v[2:3]
	v_pk_fma_f32 v[232:233], v[232:233], v[148:149], v[4:5]
	v_pk_mul_f32 v[176:177], v[230:231], v[230:231]
	v_pk_fma_f32 v[176:177], v[232:233], v[232:233], v[176:177]
	v_pk_mul_f32 v[230:231], v[230:231], v[178:179]
	v_pk_mul_f32 v[232:233], v[232:233], v[180:181]
	v_cvt_pk_f16_f32 v138, v230, v231
	v_cvt_pk_f16_f32 v139, v232, v233
	ds_write_b64 v166, v[138:139] offset:8448
	s_waitcnt lgkmcnt(7)
	v_cvt_f32_f16_e32 v230, v140
	v_cvt_f32_f16_sdwa v231, v140 dst_sel:DWORD dst_unused:UNUSED_PAD src0_sel:WORD_1
	v_cvt_f32_f16_e32 v232, v141
	v_cvt_f32_f16_sdwa v233, v141 dst_sel:DWORD dst_unused:UNUSED_PAD src0_sel:WORD_1
	v_pk_fma_f32 v[230:231], v[230:231], v[150:151], v[10:11]
	v_pk_fma_f32 v[232:233], v[232:233], v[152:153], v[12:13]
	v_pk_fma_f32 v[176:177], v[230:231], v[230:231], v[176:177]
	v_pk_fma_f32 v[176:177], v[232:233], v[232:233], v[176:177]
	v_pk_mul_f32 v[230:231], v[230:231], v[182:183]
	v_pk_mul_f32 v[232:233], v[232:233], v[184:185]
	v_cvt_pk_f16_f32 v140, v230, v231
	v_cvt_pk_f16_f32 v141, v232, v233
	ds_write_b64 v167, v[140:141] offset:8448
	s_waitcnt lgkmcnt(7)
	v_cvt_f32_f16_e32 v230, v142
	v_cvt_f32_f16_sdwa v231, v142 dst_sel:DWORD dst_unused:UNUSED_PAD src0_sel:WORD_1
	v_cvt_f32_f16_e32 v232, v143
	v_cvt_f32_f16_sdwa v233, v143 dst_sel:DWORD dst_unused:UNUSED_PAD src0_sel:WORD_1
	v_pk_fma_f32 v[230:231], v[230:231], v[154:155], v[6:7]
	v_pk_fma_f32 v[232:233], v[232:233], v[156:157], v[8:9]
	v_pk_fma_f32 v[176:177], v[230:231], v[230:231], v[176:177]
	v_pk_fma_f32 v[176:177], v[232:233], v[232:233], v[176:177]
	v_pk_mul_f32 v[230:231], v[230:231], v[186:187]
	v_pk_mul_f32 v[232:233], v[232:233], v[188:189]
	v_cvt_pk_f16_f32 v142, v230, v231
	v_cvt_pk_f16_f32 v143, v232, v233
	ds_write_b64 v168, v[142:143] offset:8448
	s_waitcnt lgkmcnt(7)
	v_cvt_f32_f16_e32 v230, v144
	v_cvt_f32_f16_sdwa v231, v144 dst_sel:DWORD dst_unused:UNUSED_PAD src0_sel:WORD_1
	v_cvt_f32_f16_e32 v232, v145
	v_cvt_f32_f16_sdwa v233, v145 dst_sel:DWORD dst_unused:UNUSED_PAD src0_sel:WORD_1
	v_pk_fma_f32 v[230:231], v[230:231], v[158:159], v[14:15]
	v_pk_fma_f32 v[232:233], v[232:233], v[160:161], v[16:17]
	v_pk_fma_f32 v[176:177], v[230:231], v[230:231], v[176:177]
	v_pk_fma_f32 v[176:177], v[232:233], v[232:233], v[176:177]
	v_pk_mul_f32 v[230:231], v[230:231], v[190:191]
	v_pk_mul_f32 v[232:233], v[232:233], v[192:193]
	v_cvt_pk_f16_f32 v144, v230, v231
	v_cvt_pk_f16_f32 v145, v232, v233
	ds_write_b64 v169, v[144:145] offset:8448
	v_add_f32_e32 v174, v174, v175
	v_add_f32_e32 v176, v176, v177
	ds_bpermute_b32 v175, v162, v174
	ds_bpermute_b32 v177, v162, v176
	s_waitcnt lgkmcnt(0)
	v_add_f32_e32 v174, v174, v175
	v_add_f32_e32 v176, v176, v177
	ds_bpermute_b32 v175, v163, v174
	ds_bpermute_b32 v177, v163, v176
	s_waitcnt lgkmcnt(0)
	v_add_f32_e32 v174, v174, v175
	v_add_f32_e32 v176, v176, v177
	v_add_u32_e32 v229, 0x2000, v164
	s_mov_b64 exec, s[2:3]
	global_store_dword v229, v174, s[18:19] offset:8
	global_store_dword v229, v176, s[18:19] offset:1032
	s_mov_b64 exec, -1
	s_waitcnt lgkmcnt(0)
	s_barrier
; template <bool HN, bool L0>
; DI void phaseC_epi(const Params& p, f32x4 (&acc)[2][2][4][2], int l, int n0, int m0) {
;     ...
;     const float* gatep = p.mod + (size_t)(l * 17 + modrow) * 3072 + 2048 + n0 + wr * 64 + fq * 4;
;     f32x4 gt[2][4];
; #pragma unroll
;     for (int ai = 0; ai < 2; ++ai)
; #pragma unroll
;       for (int m = 0; m < 4; ++m) gt[ai][m] = *(const f32x4*)(gatep + ai * 128 + m * 16);
; #pragma unroll
;     for (int ai = 0; ai < 2; ++ai)
; #pragma unroll
;       for (int g = 0; g < 4; ++g)
; #pragma unroll
;         for (int m = 0; m < 4; ++m)
; #pragma unroll
;           for (int j = 0; j < 4; ++j) acc[ai][g >> 1][m][g & 1][j] *= gt[ai][m][j];
;   }
;   __builtin_amdgcn_sched_barrier(0);
; #pragma unroll
;   for (int ai = 0; ai < 2; ++ai) {
;     const int f0 = n0 + ai * 128 + wr * 64 + fq * 4;
;     f32x4 gs[4], rgs[4];
; #pragma unroll
;     for (int m = 0; m < 4; ++m) {
;       if (!L0) {
;         const f32x4 g0 = *(const f32x4*)(p.norm_gain + (size_t)l * DM + f0 + m * 16);
;         const f32x4 s0 = *(const f32x4*)(p.mod + (size_t)(l * 17 + modrow) * 3072 + 1024 + f0 + m * 16);
; #pragma unroll
;         for (int j = 0; j < 4; ++j) rgs[m][j] = __builtin_amdgcn_rcpf(g0[j] * (1.f + s0[j]));
;       }
;       if (HN) {
;         const f32x4 g1 = *(const f32x4*)(p.norm_gain + (size_t)(l + 1) * DM + f0 + m * 16);
;         const f32x4 s1 = *(const f32x4*)(p.mod + (size_t)((l + 1) * 17 + modrow) * 3072 + 1024 + f0 + m * 16);
; #pragma unroll
;         for (int j = 0; j < 4; ++j) gs[m][j] = g1[j] * (1.f + s1[j]);
;       }
;     }
; #pragma unroll
;     for (int gp = 0; gp < 2; ++gp) {
;       f32x4 xv[2][4];
;       u32x2 xb[2][4];
; #pragma unroll
;       for (int n = 0; n < 2; ++n)
; #pragma unroll
;         for (int m = 0; m < 4; ++m) {
;           if (L0) xv[n][m] = *(const f32x4*)(xin0 + (size_t)(tok[gp * 2 + n] - rowoff) * DM + f0 + m * 16);
;           else xb[n][m] = *(const u32x2*)(p.xg + (size_t)tok[gp * 2 + n] * DM + f0 + m * 16);
;     ...
;             o[0] = pkh2(nv[0] * gs[m][0], nv[1] * gs[m][1]);
;             o[1] = pkh2(nv[2] * gs[m][2], nv[3] * gs[m][3]);
;             *(u32x2*)(p.xg + (size_t)tok[g] * DM + f0 + m * 16) = o;
	v_lshlrev_b32_e32 v229, 4, v251
	v_add_u32_e32 v0, 0x10000, v229
	ds_read_b128 v[130:133], v229 offset:0
	ds_read_b128 v[134:137], v229 offset:8192
	ds_read_b128 v[138:141], v229 offset:16384
	ds_read_b128 v[142:145], v229 offset:24576
	ds_read_b128 v[146:149], v229 offset:32768
	ds_read_b128 v[150:153], v229 offset:40960
	ds_read_b128 v[154:157], v229 offset:49152
	ds_read_b128 v[158:161], v229 offset:57344
	s_waitcnt lgkmcnt(7)
	global_store_dwordx4 v228, v[130:133], s[6:7]
	s_add_u32 s6, s6, 0x8000
	s_addc_u32 s7, s7, 0
	s_waitcnt lgkmcnt(6)
	global_store_dwordx4 v228, v[134:137], s[6:7]
	s_add_u32 s6, s6, 0x8000
	s_addc_u32 s7, s7, 0
	s_waitcnt lgkmcnt(5)
	global_store_dwordx4 v228, v[138:141], s[6:7]
	s_add_u32 s6, s6, 0x8000
	s_addc_u32 s7, s7, 0
	s_waitcnt lgkmcnt(4)
	global_store_dwordx4 v228, v[142:145], s[6:7]
	s_add_u32 s6, s6, 0x8000
	s_addc_u32 s7, s7, 0
	s_waitcnt lgkmcnt(3)
	global_store_dwordx4 v228, v[146:149], s[6:7]
	s_add_u32 s6, s6, 0x8000
	s_addc_u32 s7, s7, 0
	s_waitcnt lgkmcnt(2)
	global_store_dwordx4 v228, v[150:153], s[6:7]
	s_add_u32 s6, s6, 0x8000
	s_addc_u32 s7, s7, 0
	s_waitcnt lgkmcnt(1)
	global_store_dwordx4 v228, v[154:157], s[6:7]
	s_add_u32 s6, s6, 0x8000
	s_addc_u32 s7, s7, 0
	s_waitcnt lgkmcnt(0)
	global_store_dwordx4 v228, v[158:161], s[6:7]
	s_add_u32 s6, s6, 0x8000
	s_addc_u32 s7, s7, 0
	ds_read_b128 v[130:133], v0 offset:0
	ds_read_b128 v[134:137], v0 offset:8192
	ds_read_b128 v[138:141], v0 offset:16384
	ds_read_b128 v[142:145], v0 offset:24576
	ds_read_b128 v[146:149], v0 offset:32768
	ds_read_b128 v[150:153], v0 offset:40960
	ds_read_b128 v[154:157], v0 offset:49152
	ds_read_b128 v[158:161], v0 offset:57344
	s_waitcnt lgkmcnt(7)
	global_store_dwordx4 v228, v[130:133], s[6:7]
	s_add_u32 s6, s6, 0x8000
	s_addc_u32 s7, s7, 0
	s_waitcnt lgkmcnt(6)
	global_store_dwordx4 v228, v[134:137], s[6:7]
	s_add_u32 s6, s6, 0x8000
	s_addc_u32 s7, s7, 0
	s_waitcnt lgkmcnt(5)
	global_store_dwordx4 v228, v[138:141], s[6:7]
	s_add_u32 s6, s6, 0x8000
	s_addc_u32 s7, s7, 0
	s_waitcnt lgkmcnt(4)
	global_store_dwordx4 v228, v[142:145], s[6:7]
	s_add_u32 s6, s6, 0x8000
	s_addc_u32 s7, s7, 0
	s_waitcnt lgkmcnt(3)
	global_store_dwordx4 v228, v[146:149], s[6:7]
	s_add_u32 s6, s6, 0x8000
	s_addc_u32 s7, s7, 0
	s_waitcnt lgkmcnt(2)
	global_store_dwordx4 v228, v[150:153], s[6:7]
	s_add_u32 s6, s6, 0x8000
	s_addc_u32 s7, s7, 0
	s_waitcnt lgkmcnt(1)
	global_store_dwordx4 v228, v[154:157], s[6:7]
	s_add_u32 s6, s6, 0x8000
	s_addc_u32 s7, s7, 0
	s_waitcnt lgkmcnt(0)
	global_store_dwordx4 v228, v[158:161], s[6:7]
	s_barrier
	s_branch .LBB0_303
.Lpc_last:
	s_load_dwordx2 s[4:5], s[14:15], 0x20
	s_load_dwordx2 s[6:7], s[14:15], 0xa0
	s_load_dwordx2 s[10:11], s[14:15], 0xc8
	s_load_dwordx2 s[16:17], s[14:15], 0x80
	v_bfe_u32 v0, v251, 8, 1
	v_bfe_u32 v230, v251, 4, 2
	v_lshlrev_b32_e32 v227, 4, v230
	v_lshl_or_b32 v227, v0, 8, v227
	v_bfe_u32 v231, v251, 6, 2
	v_and_b32_e32 v232, 15, v251
	v_lshlrev_b32_e32 v228, 3, v230
	v_lshl_or_b32 v228, v0, 7, v228
	v_lshl_or_b32 v228, v232, 11, v228
	v_lshl_or_b32 v228, v231, 16, v228
	s_lshr_b32 s0, s26, 3
	s_cmp_gt_i32 s26, 0x7f
	s_cselect_b32 s0, 16, s0
	s_mul_i32 s9, s8, 17
	s_add_i32 s0, s0, s9
	s_mul_i32 s0, s0, 0x3000
	s_lshl_b32 s9, s25, 10
	s_add_u32 s0, s0, s9
	s_lshl_b32 s27, s8, 12
	s_add_u32 s27, s27, s9
	s_lshl_b32 s28, s26, 19
	s_lshl_b32 s9, s25, 9
	s_add_u32 s28, s28, s9
	s_mov_b32 s2, 0xffff
	s_mov_b32 s3, 0
	s_waitcnt lgkmcnt(0)
	s_add_u32 s10, s10, s0
	s_addc_u32 s11, s11, 0
	s_add_u32 s4, s4, s27
	s_addc_u32 s5, s5, 0
	s_add_u32 s6, s6, s28
	s_addc_u32 s7, s7, 0
	s_lshl_b32 s0, s26, 20
	s_lshl_b32 s9, s25, 10
	s_add_u32 s0, s0, s9
	s_add_u32 s16, s16, s0
	s_addc_u32 s17, s17, 0
	v_add_u32_e32 v230, 0x2000, v227
	v_add_u32_e32 v231, 0x1000, v227
	global_load_dwordx4 v[130:133], v230, s[10:11] offset:0
	global_load_dwordx4 v[134:137], v230, s[10:11] offset:64
	global_load_dwordx4 v[138:141], v230, s[10:11] offset:128
	global_load_dwordx4 v[142:145], v230, s[10:11] offset:192
	global_load_dwordx4 v[146:149], v227, s[4:5] offset:0
	global_load_dwordx4 v[150:153], v227, s[4:5] offset:64
	global_load_dwordx4 v[154:157], v227, s[4:5] offset:128
	global_load_dwordx4 v[158:161], v227, s[4:5] offset:192
	global_load_dwordx4 v[162:165], v231, s[10:11] offset:0
	global_load_dwordx4 v[166:169], v231, s[10:11] offset:64
	global_load_dwordx4 v[170:173], v231, s[10:11] offset:128
	global_load_dwordx4 v[174:177], v231, s[10:11] offset:192
	global_load_dwordx2 v[210:211], v228, s[6:7] offset:0
	global_load_dwordx2 v[212:213], v228, s[6:7] offset:32
	global_load_dwordx2 v[214:215], v228, s[6:7] offset:64
	global_load_dwordx2 v[216:217], v228, s[6:7] offset:96
	v_add_u32_e32 v229, 0x8000, v228
	global_load_dwordx2 v[218:219], v229, s[6:7] offset:0
	global_load_dwordx2 v[220:221], v229, s[6:7] offset:32
	global_load_dwordx2 v[222:223], v229, s[6:7] offset:64
	global_load_dwordx2 v[224:225], v229, s[6:7] offset:96
	s_waitcnt vmcnt(8)
; template <bool HN, bool L0>
; DI void phaseC_epi(const Params& p, f32x4 (&acc)[2][2][4][2], int l, int n0, int m0) {
;     ...
;     for (int ai = 0; ai < 2; ++ai)
; #pragma unroll
;       for (int g = 0; g < 4; ++g)
; #pragma unroll
;         for (int m = 0; m < 4; ++m)
; #pragma unroll
;           for (int j = 0; j < 4; ++j) acc[ai][g >> 1][m][g & 1][j] *= gt[ai][m][j];
;     ...
; #pragma unroll
;     for (int m = 0; m < 4; ++m) {
;       if (!L0) {
;         const f32x4 g0 = *(const f32x4*)(p.norm_gain + (size_t)l * DM + f0 + m * 16);
;         const f32x4 s0 = *(const f32x4*)(p.mod + (size_t)(l * 17 + modrow) * 3072 + 1024 + f0 + m * 16);
; #pragma unroll
;         for (int j = 0; j < 4; ++j) rgs[m][j] = __builtin_amdgcn_rcpf(g0[j] * (1.f + s0[j]));
;       }
;       if (HN) {
;         const f32x4 g1 = *(const f32x4*)(p.norm_gain + (size_t)(l + 1) * DM + f0 + m * 16);
;         const f32x4 s1 = *(const f32x4*)(p.mod + (size_t)((l + 1) * 17 + modrow) * 3072 + 1024 + f0 + m * 16);
; #pragma unroll
;         for (int j = 0; j < 4; ++j) gs[m][j] = g1[j] * (1.f + s1[j]);
;       }
;     }
; #pragma unroll
;     for (int gp = 0; gp < 2; ++gp) {
;       f32x4 xv[2][4];
;       u32x2 xb[2][4];
; #pragma unroll
;       for (int n = 0; n < 2; ++n)
; #pragma unroll
;         for (int m = 0; m < 4; ++m) {
;           if (L0) xv[n][m] = *(const f32x4*)(xin0 + (size_t)(tok[gp * 2 + n] - rowoff) * DM + f0 + m * 16);
;           else xb[n][m] = *(const u32x2*)(p.xg + (size_t)tok[gp * 2 + n] * DM + f0 + m * 16);
;         }
; #pragma unroll
;       for (int n = 0; n < 2; ++n) {
;         const int g = gp * 2 + n;
;         float ss = 0.f;
; #pragma unroll
;         for (int m = 0; m < 4; ++m) {
;           f32x4 xx;
;           if (L0) xx = xv[n][m];
;           else {
;             xx[0] = hlo(xb[n][m][0]) * rgs[m][0]; xx[1] = hhi(xb[n][m][0]) * rgs[m][1];
;             xx[2] = hlo(xb[n][m][1]) * rgs[m][2]; xx[3] = hhi(xb[n][m][1]) * rgs[m][3];
;           }
;           f32x4 nv;
; #pragma unroll
;           for (int j = 0; j < 4; ++j) { nv[j] = xx[j] + acc[ai][gp][m][n][j]; ss += nv[j] * nv[j]; }
;           if (HN) {
;             u32x2 o;
;             o[0] = pkh2(nv[0] * gs[m][0], nv[1] * gs[m][1]);
;             o[1] = pkh2(nv[2] * gs[m][2], nv[3] * gs[m][3]);
;             *(u32x2*)(p.xg + (size_t)tok[g] * DM + f0 + m * 16) = o;
;           } else {
	v_add_f32_e32 v162, 1.0, v162
	v_add_f32_e32 v163, 1.0, v163
	v_pk_mul_f32 v[146:147], v[146:147], v[162:163]
	v_add_f32_e32 v164, 1.0, v164
	v_add_f32_e32 v165, 1.0, v165
	v_pk_mul_f32 v[148:149], v[148:149], v[164:165]
	v_add_f32_e32 v166, 1.0, v166
	v_add_f32_e32 v167, 1.0, v167
	v_pk_mul_f32 v[150:151], v[150:151], v[166:167]
	v_add_f32_e32 v168, 1.0, v168
	v_add_f32_e32 v169, 1.0, v169
	v_pk_mul_f32 v[152:153], v[152:153], v[168:169]
	v_add_f32_e32 v170, 1.0, v170
	v_add_f32_e32 v171, 1.0, v171
	v_pk_mul_f32 v[154:155], v[154:155], v[170:171]
	v_add_f32_e32 v172, 1.0, v172
	v_add_f32_e32 v173, 1.0, v173
	v_pk_mul_f32 v[156:157], v[156:157], v[172:173]
	v_add_f32_e32 v174, 1.0, v174
	v_add_f32_e32 v175, 1.0, v175
	v_pk_mul_f32 v[158:159], v[158:159], v[174:175]
	v_add_f32_e32 v176, 1.0, v176
	v_add_f32_e32 v177, 1.0, v177
	v_pk_mul_f32 v[160:161], v[160:161], v[176:177]
	v_rcp_f32_e32 v146, v146
	v_rcp_f32_e32 v147, v147
	v_rcp_f32_e32 v148, v148
	v_rcp_f32_e32 v149, v149
	v_rcp_f32_e32 v150, v150
	v_rcp_f32_e32 v151, v151
	v_rcp_f32_e32 v152, v152
	v_rcp_f32_e32 v153, v153
	v_rcp_f32_e32 v154, v154
	v_rcp_f32_e32 v155, v155
	v_rcp_f32_e32 v156, v156
	v_rcp_f32_e32 v157, v157
	v_rcp_f32_e32 v158, v158
	v_rcp_f32_e32 v159, v159
	v_rcp_f32_e32 v160, v160
	v_rcp_f32_e32 v161, v161
	v_pk_mul_f32 v[126:127], v[126:127], v[130:131]
	v_pk_mul_f32 v[128:129], v[128:129], v[132:133]
	v_pk_mul_f32 v[102:103], v[102:103], v[130:131]
	v_pk_mul_f32 v[104:105], v[104:105], v[132:133]
	v_pk_mul_f32 v[122:123], v[122:123], v[134:135]
	v_pk_mul_f32 v[124:125], v[124:125], v[136:137]
	v_pk_mul_f32 v[98:99], v[98:99], v[134:135]
	v_pk_mul_f32 v[100:101], v[100:101], v[136:137]
	v_pk_mul_f32 v[118:119], v[118:119], v[138:139]
	v_pk_mul_f32 v[120:121], v[120:121], v[140:141]
	v_pk_mul_f32 v[106:107], v[106:107], v[138:139]
	v_pk_mul_f32 v[108:109], v[108:109], v[140:141]
	v_pk_mul_f32 v[114:115], v[114:115], v[142:143]
	v_pk_mul_f32 v[116:117], v[116:117], v[144:145]
	v_pk_mul_f32 v[110:111], v[110:111], v[142:143]
	v_pk_mul_f32 v[112:113], v[112:113], v[144:145]
	v_pk_mul_f32 v[82:83], v[82:83], v[130:131]
	v_pk_mul_f32 v[84:85], v[84:85], v[132:133]
	v_pk_mul_f32 v[66:67], v[66:67], v[130:131]
	v_pk_mul_f32 v[68:69], v[68:69], v[132:133]
	v_pk_mul_f32 v[86:87], v[86:87], v[134:135]
	v_pk_mul_f32 v[88:89], v[88:89], v[136:137]
	v_pk_mul_f32 v[74:75], v[74:75], v[134:135]
	v_pk_mul_f32 v[76:77], v[76:77], v[136:137]
	v_pk_mul_f32 v[90:91], v[90:91], v[138:139]
	v_pk_mul_f32 v[92:93], v[92:93], v[140:141]
	v_pk_mul_f32 v[70:71], v[70:71], v[138:139]
	v_pk_mul_f32 v[72:73], v[72:73], v[140:141]
	v_pk_mul_f32 v[94:95], v[94:95], v[142:143]
	v_pk_mul_f32 v[96:97], v[96:97], v[144:145]
	v_pk_mul_f32 v[78:79], v[78:79], v[142:143]
	v_pk_mul_f32 v[80:81], v[80:81], v[144:145]
	v_add_u32_e32 v229, 0x40000, v228
	global_load_dwordx2 v[130:131], v229, s[6:7] offset:0
	global_load_dwordx2 v[132:133], v229, s[6:7] offset:32
	global_load_dwordx2 v[134:135], v229, s[6:7] offset:64
	global_load_dwordx2 v[136:137], v229, s[6:7] offset:96
	v_add_u32_e32 v229, 0x48000, v228
	global_load_dwordx2 v[138:139], v229, s[6:7] offset:0
	global_load_dwordx2 v[140:141], v229, s[6:7] offset:32
	global_load_dwordx2 v[142:143], v229, s[6:7] offset:64
	global_load_dwordx2 v[144:145], v229, s[6:7] offset:96
	v_add_u32_e32 v229, 0x0, v228
	v_lshlrev_b32_e32 v229, 1, v229
	s_waitcnt vmcnt(15)
	v_cvt_f32_f16_e32 v194, v210
	v_cvt_f32_f16_sdwa v195, v210 dst_sel:DWORD dst_unused:UNUSED_PAD src0_sel:WORD_1
	v_cvt_f32_f16_e32 v196, v211
	v_cvt_f32_f16_sdwa v197, v211 dst_sel:DWORD dst_unused:UNUSED_PAD src0_sel:WORD_1
	v_pk_fma_f32 v[194:195], v[194:195], v[146:147], v[126:127]
	v_pk_fma_f32 v[196:197], v[196:197], v[148:149], v[128:129]
	global_store_dwordx4 v229, v[194:197], s[16:17] offset:0
	s_waitcnt vmcnt(15)
	v_cvt_f32_f16_e32 v198, v212
	v_cvt_f32_f16_sdwa v199, v212 dst_sel:DWORD dst_unused:UNUSED_PAD src0_sel:WORD_1
	v_cvt_f32_f16_e32 v200, v213
	v_cvt_f32_f16_sdwa v201, v213 dst_sel:DWORD dst_unused:UNUSED_PAD src0_sel:WORD_1
	v_pk_fma_f32 v[198:199], v[198:199], v[150:151], v[122:123]
	v_pk_fma_f32 v[200:201], v[200:201], v[152:153], v[124:125]
	global_store_dwordx4 v229, v[198:201], s[16:17] offset:64
	s_waitcnt vmcnt(15)
	v_cvt_f32_f16_e32 v202, v214
	v_cvt_f32_f16_sdwa v203, v214 dst_sel:DWORD dst_unused:UNUSED_PAD src0_sel:WORD_1
	v_cvt_f32_f16_e32 v204, v215
	v_cvt_f32_f16_sdwa v205, v215 dst_sel:DWORD dst_unused:UNUSED_PAD src0_sel:WORD_1
	v_pk_fma_f32 v[202:203], v[202:203], v[154:155], v[118:119]
	v_pk_fma_f32 v[204:205], v[204:205], v[156:157], v[120:121]
	global_store_dwordx4 v229, v[202:205], s[16:17] offset:128
	s_waitcnt vmcnt(15)
	v_cvt_f32_f16_e32 v206, v216
	v_cvt_f32_f16_sdwa v207, v216 dst_sel:DWORD dst_unused:UNUSED_PAD src0_sel:WORD_1
	v_cvt_f32_f16_e32 v208, v217
	v_cvt_f32_f16_sdwa v209, v217 dst_sel:DWORD dst_unused:UNUSED_PAD src0_sel:WORD_1
	v_pk_fma_f32 v[206:207], v[206:207], v[158:159], v[114:115]
	v_pk_fma_f32 v[208:209], v[208:209], v[160:161], v[116:117]
	global_store_dwordx4 v229, v[206:209], s[16:17] offset:192
	v_add_u32_e32 v229, 0x8000, v228
	v_lshlrev_b32_e32 v229, 1, v229
	s_waitcnt vmcnt(15)
	v_cvt_f32_f16_e32 v202, v218
	v_cvt_f32_f16_sdwa v203, v218 dst_sel:DWORD dst_unused:UNUSED_PAD src0_sel:WORD_1
	v_cvt_f32_f16_e32 v204, v219
	v_cvt_f32_f16_sdwa v205, v219 dst_sel:DWORD dst_unused:UNUSED_PAD src0_sel:WORD_1
	v_pk_fma_f32 v[202:203], v[202:203], v[146:147], v[102:103]
	v_pk_fma_f32 v[204:205], v[204:205], v[148:149], v[104:105]
	global_store_dwordx4 v229, v[202:205], s[16:17] offset:0
	s_waitcnt vmcnt(15)
; DI float hlo(unsigned u) { const h2_t v = __builtin_bit_cast(h2_t, u); return (float)v[0]; }
; DI float hhi(unsigned u) { const h2_t v = __builtin_bit_cast(h2_t, u); return (float)v[1]; }
; template <bool HN, bool L0>
; DI void phaseC_epi(const Params& p, f32x4 (&acc)[2][2][4][2], int l, int n0, int m0) {
;     ...
;       for (int n = 0; n < 2; ++n)
; #pragma unroll
;         for (int m = 0; m < 4; ++m) {
;           if (L0) xv[n][m] = *(const f32x4*)(xin0 + (size_t)(tok[gp * 2 + n] - rowoff) * DM + f0 + m * 16);
;           else xb[n][m] = *(const u32x2*)(p.xg + (size_t)tok[gp * 2 + n] * DM + f0 + m * 16);
;         }
; #pragma unroll
;       for (int n = 0; n < 2; ++n) {
;         const int g = gp * 2 + n;
;         float ss = 0.f;
; #pragma unroll
;         for (int m = 0; m < 4; ++m) {
;           f32x4 xx;
;           if (L0) xx = xv[n][m];
;           else {
;             xx[0] = hlo(xb[n][m][0]) * rgs[m][0]; xx[1] = hhi(xb[n][m][0]) * rgs[m][1];
;             xx[2] = hlo(xb[n][m][1]) * rgs[m][2]; xx[3] = hhi(xb[n][m][1]) * rgs[m][3];
;           }
;           f32x4 nv;
; #pragma unroll
;           for (int j = 0; j < 4; ++j) { nv[j] = xx[j] + acc[ai][gp][m][n][j]; ss += nv[j] * nv[j]; }
;           if (HN) {
;             u32x2 o;
;             o[0] = pkh2(nv[0] * gs[m][0], nv[1] * gs[m][1]);
;             o[1] = pkh2(nv[2] * gs[m][2], nv[3] * gs[m][3]);
;             *(u32x2*)(p.xg + (size_t)tok[g] * DM + f0 + m * 16) = o;
;           } else {
;             *(f32x4*)(p.out + (size_t)tok[g] * DM + f0 + m * 16) = nv;
	v_cvt_f32_f16_e32 v206, v220
	v_cvt_f32_f16_sdwa v207, v220 dst_sel:DWORD dst_unused:UNUSED_PAD src0_sel:WORD_1
	v_cvt_f32_f16_e32 v208, v221
	v_cvt_f32_f16_sdwa v209, v221 dst_sel:DWORD dst_unused:UNUSED_PAD src0_sel:WORD_1
	v_pk_fma_f32 v[206:207], v[206:207], v[150:151], v[98:99]
	v_pk_fma_f32 v[208:209], v[208:209], v[152:153], v[100:101]
	global_store_dwordx4 v229, v[206:209], s[16:17] offset:64
	s_waitcnt vmcnt(15)
	v_cvt_f32_f16_e32 v194, v222
	v_cvt_f32_f16_sdwa v195, v222 dst_sel:DWORD dst_unused:UNUSED_PAD src0_sel:WORD_1
	v_cvt_f32_f16_e32 v196, v223
	v_cvt_f32_f16_sdwa v197, v223 dst_sel:DWORD dst_unused:UNUSED_PAD src0_sel:WORD_1
	v_pk_fma_f32 v[194:195], v[194:195], v[154:155], v[106:107]
	v_pk_fma_f32 v[196:197], v[196:197], v[156:157], v[108:109]
	global_store_dwordx4 v229, v[194:197], s[16:17] offset:128
	s_waitcnt vmcnt(15)
	v_cvt_f32_f16_e32 v198, v224
	v_cvt_f32_f16_sdwa v199, v224 dst_sel:DWORD dst_unused:UNUSED_PAD src0_sel:WORD_1
	v_cvt_f32_f16_e32 v200, v225
	v_cvt_f32_f16_sdwa v201, v225 dst_sel:DWORD dst_unused:UNUSED_PAD src0_sel:WORD_1
	v_pk_fma_f32 v[198:199], v[198:199], v[158:159], v[110:111]
	v_pk_fma_f32 v[200:201], v[200:201], v[160:161], v[112:113]
	global_store_dwordx4 v229, v[198:201], s[16:17] offset:192
	v_add_u32_e32 v229, 0x40000, v228
	v_lshlrev_b32_e32 v229, 1, v229
	s_waitcnt vmcnt(15)
	v_cvt_f32_f16_e32 v194, v130
	v_cvt_f32_f16_sdwa v195, v130 dst_sel:DWORD dst_unused:UNUSED_PAD src0_sel:WORD_1
	v_cvt_f32_f16_e32 v196, v131
	v_cvt_f32_f16_sdwa v197, v131 dst_sel:DWORD dst_unused:UNUSED_PAD src0_sel:WORD_1
	v_pk_fma_f32 v[194:195], v[194:195], v[146:147], v[82:83]
	v_pk_fma_f32 v[196:197], v[196:197], v[148:149], v[84:85]
	global_store_dwordx4 v229, v[194:197], s[16:17] offset:0
	s_waitcnt vmcnt(15)
	v_cvt_f32_f16_e32 v198, v132
	v_cvt_f32_f16_sdwa v199, v132 dst_sel:DWORD dst_unused:UNUSED_PAD src0_sel:WORD_1
	v_cvt_f32_f16_e32 v200, v133
	v_cvt_f32_f16_sdwa v201, v133 dst_sel:DWORD dst_unused:UNUSED_PAD src0_sel:WORD_1
	v_pk_fma_f32 v[198:199], v[198:199], v[150:151], v[86:87]
	v_pk_fma_f32 v[200:201], v[200:201], v[152:153], v[88:89]
	global_store_dwordx4 v229, v[198:201], s[16:17] offset:64
	s_waitcnt vmcnt(15)
	v_cvt_f32_f16_e32 v202, v134
	v_cvt_f32_f16_sdwa v203, v134 dst_sel:DWORD dst_unused:UNUSED_PAD src0_sel:WORD_1
	v_cvt_f32_f16_e32 v204, v135
	v_cvt_f32_f16_sdwa v205, v135 dst_sel:DWORD dst_unused:UNUSED_PAD src0_sel:WORD_1
	v_pk_fma_f32 v[202:203], v[202:203], v[154:155], v[90:91]
	v_pk_fma_f32 v[204:205], v[204:205], v[156:157], v[92:93]
	global_store_dwordx4 v229, v[202:205], s[16:17] offset:128
	s_waitcnt vmcnt(15)
	v_cvt_f32_f16_e32 v206, v136
	v_cvt_f32_f16_sdwa v207, v136 dst_sel:DWORD dst_unused:UNUSED_PAD src0_sel:WORD_1
	v_cvt_f32_f16_e32 v208, v137
	v_cvt_f32_f16_sdwa v209, v137 dst_sel:DWORD dst_unused:UNUSED_PAD src0_sel:WORD_1
	v_pk_fma_f32 v[206:207], v[206:207], v[158:159], v[94:95]
	v_pk_fma_f32 v[208:209], v[208:209], v[160:161], v[96:97]
	global_store_dwordx4 v229, v[206:209], s[16:17] offset:192
	v_add_u32_e32 v229, 0x48000, v228
	v_lshlrev_b32_e32 v229, 1, v229
	s_waitcnt vmcnt(15)
	v_cvt_f32_f16_e32 v202, v138
	v_cvt_f32_f16_sdwa v203, v138 dst_sel:DWORD dst_unused:UNUSED_PAD src0_sel:WORD_1
	v_cvt_f32_f16_e32 v204, v139
	v_cvt_f32_f16_sdwa v205, v139 dst_sel:DWORD dst_unused:UNUSED_PAD src0_sel:WORD_1
	v_pk_fma_f32 v[202:203], v[202:203], v[146:147], v[66:67]
	v_pk_fma_f32 v[204:205], v[204:205], v[148:149], v[68:69]
	global_store_dwordx4 v229, v[202:205], s[16:17] offset:0
	s_waitcnt vmcnt(15)
	v_cvt_f32_f16_e32 v206, v140
	v_cvt_f32_f16_sdwa v207, v140 dst_sel:DWORD dst_unused:UNUSED_PAD src0_sel:WORD_1
	v_cvt_f32_f16_e32 v208, v141
	v_cvt_f32_f16_sdwa v209, v141 dst_sel:DWORD dst_unused:UNUSED_PAD src0_sel:WORD_1
	v_pk_fma_f32 v[206:207], v[206:207], v[150:151], v[74:75]
	v_pk_fma_f32 v[208:209], v[208:209], v[152:153], v[76:77]
	global_store_dwordx4 v229, v[206:209], s[16:17] offset:64
	s_waitcnt vmcnt(15)
	v_cvt_f32_f16_e32 v194, v142
	v_cvt_f32_f16_sdwa v195, v142 dst_sel:DWORD dst_unused:UNUSED_PAD src0_sel:WORD_1
	v_cvt_f32_f16_e32 v196, v143
	v_cvt_f32_f16_sdwa v197, v143 dst_sel:DWORD dst_unused:UNUSED_PAD src0_sel:WORD_1
	v_pk_fma_f32 v[194:195], v[194:195], v[154:155], v[70:71]
	v_pk_fma_f32 v[196:197], v[196:197], v[156:157], v[72:73]
	global_store_dwordx4 v229, v[194:197], s[16:17] offset:128
	s_waitcnt vmcnt(15)
	v_cvt_f32_f16_e32 v198, v144
	v_cvt_f32_f16_sdwa v199, v144 dst_sel:DWORD dst_unused:UNUSED_PAD src0_sel:WORD_1
	v_cvt_f32_f16_e32 v200, v145
	v_cvt_f32_f16_sdwa v201, v145 dst_sel:DWORD dst_unused:UNUSED_PAD src0_sel:WORD_1
	v_pk_fma_f32 v[198:199], v[198:199], v[158:159], v[78:79]
	v_pk_fma_f32 v[200:201], v[200:201], v[160:161], v[80:81]
	global_store_dwordx4 v229, v[198:201], s[16:17] offset:192
	v_add_u32_e32 v230, 0x2000, v227
	v_add_u32_e32 v231, 0x1000, v227
	global_load_dwordx4 v[130:133], v230, s[10:11] offset:512
	global_load_dwordx4 v[134:137], v230, s[10:11] offset:576
	global_load_dwordx4 v[138:141], v230, s[10:11] offset:640
	global_load_dwordx4 v[142:145], v230, s[10:11] offset:704
	global_load_dwordx4 v[146:149], v227, s[4:5] offset:512
	global_load_dwordx4 v[150:153], v227, s[4:5] offset:576
	global_load_dwordx4 v[154:157], v227, s[4:5] offset:640
	global_load_dwordx4 v[158:161], v227, s[4:5] offset:704
	global_load_dwordx4 v[162:165], v231, s[10:11] offset:512
	global_load_dwordx4 v[166:169], v231, s[10:11] offset:576
	global_load_dwordx4 v[170:173], v231, s[10:11] offset:640
	global_load_dwordx4 v[174:177], v231, s[10:11] offset:704
	global_load_dwordx2 v[210:211], v228, s[6:7] offset:256
	global_load_dwordx2 v[212:213], v228, s[6:7] offset:288
	global_load_dwordx2 v[214:215], v228, s[6:7] offset:320
	global_load_dwordx2 v[216:217], v228, s[6:7] offset:352
	v_add_u32_e32 v229, 0x8000, v228
	global_load_dwordx2 v[218:219], v229, s[6:7] offset:256
	global_load_dwordx2 v[220:221], v229, s[6:7] offset:288
	global_load_dwordx2 v[222:223], v229, s[6:7] offset:320
	global_load_dwordx2 v[224:225], v229, s[6:7] offset:352
	s_waitcnt vmcnt(8)
; DI float hlo(unsigned u) { const h2_t v = __builtin_bit_cast(h2_t, u); return (float)v[0]; }
; DI float hhi(unsigned u) { const h2_t v = __builtin_bit_cast(h2_t, u); return (float)v[1]; }
; template <bool HN, bool L0>
; DI void phaseC_epi(const Params& p, f32x4 (&acc)[2][2][4][2], int l, int n0, int m0) {
;     ...
; #pragma unroll
;     for (int m = 0; m < 4; ++m) {
;       if (!L0) {
;         const f32x4 g0 = *(const f32x4*)(p.norm_gain + (size_t)l * DM + f0 + m * 16);
;         const f32x4 s0 = *(const f32x4*)(p.mod + (size_t)(l * 17 + modrow) * 3072 + 1024 + f0 + m * 16);
; #pragma unroll
;         for (int j = 0; j < 4; ++j) rgs[m][j] = __builtin_amdgcn_rcpf(g0[j] * (1.f + s0[j]));
;       }
;       if (HN) {
;         const f32x4 g1 = *(const f32x4*)(p.norm_gain + (size_t)(l + 1) * DM + f0 + m * 16);
;         const f32x4 s1 = *(const f32x4*)(p.mod + (size_t)((l + 1) * 17 + modrow) * 3072 + 1024 + f0 + m * 16);
; #pragma unroll
;         for (int j = 0; j < 4; ++j) gs[m][j] = g1[j] * (1.f + s1[j]);
;       }
;     }
; #pragma unroll
;     for (int gp = 0; gp < 2; ++gp) {
;       f32x4 xv[2][4];
;       u32x2 xb[2][4];
; #pragma unroll
;       for (int n = 0; n < 2; ++n)
; #pragma unroll
;         for (int m = 0; m < 4; ++m) {
;           if (L0) xv[n][m] = *(const f32x4*)(xin0 + (size_t)(tok[gp * 2 + n] - rowoff) * DM + f0 + m * 16);
;           else xb[n][m] = *(const u32x2*)(p.xg + (size_t)tok[gp * 2 + n] * DM + f0 + m * 16);
;         }
; #pragma unroll
;       for (int n = 0; n < 2; ++n) {
;         const int g = gp * 2 + n;
;         float ss = 0.f;
; #pragma unroll
;         for (int m = 0; m < 4; ++m) {
;           f32x4 xx;
;           if (L0) xx = xv[n][m];
;           else {
;             xx[0] = hlo(xb[n][m][0]) * rgs[m][0]; xx[1] = hhi(xb[n][m][0]) * rgs[m][1];
;             xx[2] = hlo(xb[n][m][1]) * rgs[m][2]; xx[3] = hhi(xb[n][m][1]) * rgs[m][3];
;           }
;           f32x4 nv;
; #pragma unroll
;           for (int j = 0; j < 4; ++j) { nv[j] = xx[j] + acc[ai][gp][m][n][j]; ss += nv[j] * nv[j]; }
;           if (HN) {
;             u32x2 o;
;             o[0] = pkh2(nv[0] * gs[m][0], nv[1] * gs[m][1]);
;             o[1] = pkh2(nv[2] * gs[m][2], nv[3] * gs[m][3]);
;             *(u32x2*)(p.xg + (size_t)tok[g] * DM + f0 + m * 16) = o;
;           } else {
;             *(f32x4*)(p.out + (size_t)tok[g] * DM + f0 + m * 16) = nv;
	v_add_f32_e32 v162, 1.0, v162
	v_add_f32_e32 v163, 1.0, v163
	v_pk_mul_f32 v[146:147], v[146:147], v[162:163]
	v_add_f32_e32 v164, 1.0, v164
	v_add_f32_e32 v165, 1.0, v165
	v_pk_mul_f32 v[148:149], v[148:149], v[164:165]
	v_add_f32_e32 v166, 1.0, v166
	v_add_f32_e32 v167, 1.0, v167
	v_pk_mul_f32 v[150:151], v[150:151], v[166:167]
	v_add_f32_e32 v168, 1.0, v168
	v_add_f32_e32 v169, 1.0, v169
	v_pk_mul_f32 v[152:153], v[152:153], v[168:169]
	v_add_f32_e32 v170, 1.0, v170
	v_add_f32_e32 v171, 1.0, v171
	v_pk_mul_f32 v[154:155], v[154:155], v[170:171]
	v_add_f32_e32 v172, 1.0, v172
	v_add_f32_e32 v173, 1.0, v173
	v_pk_mul_f32 v[156:157], v[156:157], v[172:173]
	v_add_f32_e32 v174, 1.0, v174
	v_add_f32_e32 v175, 1.0, v175
	v_pk_mul_f32 v[158:159], v[158:159], v[174:175]
	v_add_f32_e32 v176, 1.0, v176
	v_add_f32_e32 v177, 1.0, v177
	v_pk_mul_f32 v[160:161], v[160:161], v[176:177]
	v_rcp_f32_e32 v146, v146
	v_rcp_f32_e32 v147, v147
	v_rcp_f32_e32 v148, v148
	v_rcp_f32_e32 v149, v149
	v_rcp_f32_e32 v150, v150
	v_rcp_f32_e32 v151, v151
	v_rcp_f32_e32 v152, v152
	v_rcp_f32_e32 v153, v153
	v_rcp_f32_e32 v154, v154
	v_rcp_f32_e32 v155, v155
	v_rcp_f32_e32 v156, v156
	v_rcp_f32_e32 v157, v157
	v_rcp_f32_e32 v158, v158
	v_rcp_f32_e32 v159, v159
	v_rcp_f32_e32 v160, v160
	v_rcp_f32_e32 v161, v161
	v_pk_mul_f32 v[50:51], v[50:51], v[130:131]
	v_pk_mul_f32 v[52:53], v[52:53], v[132:133]
	v_pk_mul_f32 v[34:35], v[34:35], v[130:131]
	v_pk_mul_f32 v[36:37], v[36:37], v[132:133]
	v_pk_mul_f32 v[54:55], v[54:55], v[134:135]
	v_pk_mul_f32 v[56:57], v[56:57], v[136:137]
	v_pk_mul_f32 v[38:39], v[38:39], v[134:135]
	v_pk_mul_f32 v[40:41], v[40:41], v[136:137]
	v_pk_mul_f32 v[58:59], v[58:59], v[138:139]
	v_pk_mul_f32 v[60:61], v[60:61], v[140:141]
	v_pk_mul_f32 v[42:43], v[42:43], v[138:139]
	v_pk_mul_f32 v[44:45], v[44:45], v[140:141]
	v_pk_mul_f32 v[62:63], v[62:63], v[142:143]
	v_pk_mul_f32 v[64:65], v[64:65], v[144:145]
	v_pk_mul_f32 v[46:47], v[46:47], v[142:143]
	v_pk_mul_f32 v[48:49], v[48:49], v[144:145]
	v_pk_mul_f32 v[18:19], v[18:19], v[130:131]
	v_pk_mul_f32 v[20:21], v[20:21], v[132:133]
	v_pk_mul_f32 v[2:3], v[2:3], v[130:131]
	v_pk_mul_f32 v[4:5], v[4:5], v[132:133]
	v_pk_mul_f32 v[22:23], v[22:23], v[134:135]
	v_pk_mul_f32 v[24:25], v[24:25], v[136:137]
	v_pk_mul_f32 v[10:11], v[10:11], v[134:135]
	v_pk_mul_f32 v[12:13], v[12:13], v[136:137]
	v_pk_mul_f32 v[26:27], v[26:27], v[138:139]
	v_pk_mul_f32 v[28:29], v[28:29], v[140:141]
	v_pk_mul_f32 v[6:7], v[6:7], v[138:139]
	v_pk_mul_f32 v[8:9], v[8:9], v[140:141]
	v_pk_mul_f32 v[30:31], v[30:31], v[142:143]
	v_pk_mul_f32 v[32:33], v[32:33], v[144:145]
	v_pk_mul_f32 v[14:15], v[14:15], v[142:143]
	v_pk_mul_f32 v[16:17], v[16:17], v[144:145]
	v_add_u32_e32 v229, 0x40000, v228
	global_load_dwordx2 v[130:131], v229, s[6:7] offset:256
	global_load_dwordx2 v[132:133], v229, s[6:7] offset:288
	global_load_dwordx2 v[134:135], v229, s[6:7] offset:320
	global_load_dwordx2 v[136:137], v229, s[6:7] offset:352
	v_add_u32_e32 v229, 0x48000, v228
	global_load_dwordx2 v[138:139], v229, s[6:7] offset:256
	global_load_dwordx2 v[140:141], v229, s[6:7] offset:288
	global_load_dwordx2 v[142:143], v229, s[6:7] offset:320
	global_load_dwordx2 v[144:145], v229, s[6:7] offset:352
	v_add_u32_e32 v229, 0x0, v228
	v_lshlrev_b32_e32 v229, 1, v229
	s_waitcnt vmcnt(15)
	v_cvt_f32_f16_e32 v194, v210
	v_cvt_f32_f16_sdwa v195, v210 dst_sel:DWORD dst_unused:UNUSED_PAD src0_sel:WORD_1
	v_cvt_f32_f16_e32 v196, v211
	v_cvt_f32_f16_sdwa v197, v211 dst_sel:DWORD dst_unused:UNUSED_PAD src0_sel:WORD_1
	v_pk_fma_f32 v[194:195], v[194:195], v[146:147], v[50:51]
	v_pk_fma_f32 v[196:197], v[196:197], v[148:149], v[52:53]
	global_store_dwordx4 v229, v[194:197], s[16:17] offset:512
	s_waitcnt vmcnt(15)
	v_cvt_f32_f16_e32 v198, v212
	v_cvt_f32_f16_sdwa v199, v212 dst_sel:DWORD dst_unused:UNUSED_PAD src0_sel:WORD_1
	v_cvt_f32_f16_e32 v200, v213
	v_cvt_f32_f16_sdwa v201, v213 dst_sel:DWORD dst_unused:UNUSED_PAD src0_sel:WORD_1
	v_pk_fma_f32 v[198:199], v[198:199], v[150:151], v[54:55]
	v_pk_fma_f32 v[200:201], v[200:201], v[152:153], v[56:57]
	global_store_dwordx4 v229, v[198:201], s[16:17] offset:576
	s_waitcnt vmcnt(15)
	v_cvt_f32_f16_e32 v202, v214
	v_cvt_f32_f16_sdwa v203, v214 dst_sel:DWORD dst_unused:UNUSED_PAD src0_sel:WORD_1
	v_cvt_f32_f16_e32 v204, v215
	v_cvt_f32_f16_sdwa v205, v215 dst_sel:DWORD dst_unused:UNUSED_PAD src0_sel:WORD_1
	v_pk_fma_f32 v[202:203], v[202:203], v[154:155], v[58:59]
	v_pk_fma_f32 v[204:205], v[204:205], v[156:157], v[60:61]
	global_store_dwordx4 v229, v[202:205], s[16:17] offset:640
	s_waitcnt vmcnt(15)
	v_cvt_f32_f16_e32 v206, v216
	v_cvt_f32_f16_sdwa v207, v216 dst_sel:DWORD dst_unused:UNUSED_PAD src0_sel:WORD_1
	v_cvt_f32_f16_e32 v208, v217
	v_cvt_f32_f16_sdwa v209, v217 dst_sel:DWORD dst_unused:UNUSED_PAD src0_sel:WORD_1
	v_pk_fma_f32 v[206:207], v[206:207], v[158:159], v[62:63]
	v_pk_fma_f32 v[208:209], v[208:209], v[160:161], v[64:65]
	global_store_dwordx4 v229, v[206:209], s[16:17] offset:704
	v_add_u32_e32 v229, 0x8000, v228
	v_lshlrev_b32_e32 v229, 1, v229
	s_waitcnt vmcnt(15)
; DI float hlo(unsigned u) { const h2_t v = __builtin_bit_cast(h2_t, u); return (float)v[0]; }
; DI float hhi(unsigned u) { const h2_t v = __builtin_bit_cast(h2_t, u); return (float)v[1]; }
; template <bool HN, bool L0>
; DI void phaseC_epi(const Params& p, f32x4 (&acc)[2][2][4][2], int l, int n0, int m0) {
;     ...
;       for (int n = 0; n < 2; ++n) {
;         const int g = gp * 2 + n;
;         float ss = 0.f;
; #pragma unroll
;         for (int m = 0; m < 4; ++m) {
;           f32x4 xx;
;           if (L0) xx = xv[n][m];
;           else {
;             xx[0] = hlo(xb[n][m][0]) * rgs[m][0]; xx[1] = hhi(xb[n][m][0]) * rgs[m][1];
;             xx[2] = hlo(xb[n][m][1]) * rgs[m][2]; xx[3] = hhi(xb[n][m][1]) * rgs[m][3];
;           }
;           f32x4 nv;
; #pragma unroll
;           for (int j = 0; j < 4; ++j) { nv[j] = xx[j] + acc[ai][gp][m][n][j]; ss += nv[j] * nv[j]; }
;           if (HN) {
;             u32x2 o;
;             o[0] = pkh2(nv[0] * gs[m][0], nv[1] * gs[m][1]);
;             o[1] = pkh2(nv[2] * gs[m][2], nv[3] * gs[m][3]);
;             *(u32x2*)(p.xg + (size_t)tok[g] * DM + f0 + m * 16) = o;
;           } else {
;             *(f32x4*)(p.out + (size_t)tok[g] * DM + f0 + m * 16) = nv;
	v_cvt_f32_f16_e32 v202, v218
	v_cvt_f32_f16_sdwa v203, v218 dst_sel:DWORD dst_unused:UNUSED_PAD src0_sel:WORD_1
	v_cvt_f32_f16_e32 v204, v219
	v_cvt_f32_f16_sdwa v205, v219 dst_sel:DWORD dst_unused:UNUSED_PAD src0_sel:WORD_1
	v_pk_fma_f32 v[202:203], v[202:203], v[146:147], v[34:35]
	v_pk_fma_f32 v[204:205], v[204:205], v[148:149], v[36:37]
	global_store_dwordx4 v229, v[202:205], s[16:17] offset:512
	s_waitcnt vmcnt(15)
	v_cvt_f32_f16_e32 v206, v220
	v_cvt_f32_f16_sdwa v207, v220 dst_sel:DWORD dst_unused:UNUSED_PAD src0_sel:WORD_1
	v_cvt_f32_f16_e32 v208, v221
	v_cvt_f32_f16_sdwa v209, v221 dst_sel:DWORD dst_unused:UNUSED_PAD src0_sel:WORD_1
	v_pk_fma_f32 v[206:207], v[206:207], v[150:151], v[38:39]
	v_pk_fma_f32 v[208:209], v[208:209], v[152:153], v[40:41]
	global_store_dwordx4 v229, v[206:209], s[16:17] offset:576
	s_waitcnt vmcnt(15)
	v_cvt_f32_f16_e32 v194, v222
	v_cvt_f32_f16_sdwa v195, v222 dst_sel:DWORD dst_unused:UNUSED_PAD src0_sel:WORD_1
	v_cvt_f32_f16_e32 v196, v223
	v_cvt_f32_f16_sdwa v197, v223 dst_sel:DWORD dst_unused:UNUSED_PAD src0_sel:WORD_1
	v_pk_fma_f32 v[194:195], v[194:195], v[154:155], v[42:43]
	v_pk_fma_f32 v[196:197], v[196:197], v[156:157], v[44:45]
	global_store_dwordx4 v229, v[194:197], s[16:17] offset:640
	s_waitcnt vmcnt(15)
	v_cvt_f32_f16_e32 v198, v224
	v_cvt_f32_f16_sdwa v199, v224 dst_sel:DWORD dst_unused:UNUSED_PAD src0_sel:WORD_1
	v_cvt_f32_f16_e32 v200, v225
	v_cvt_f32_f16_sdwa v201, v225 dst_sel:DWORD dst_unused:UNUSED_PAD src0_sel:WORD_1
	v_pk_fma_f32 v[198:199], v[198:199], v[158:159], v[46:47]
	v_pk_fma_f32 v[200:201], v[200:201], v[160:161], v[48:49]
	global_store_dwordx4 v229, v[198:201], s[16:17] offset:704
	v_add_u32_e32 v229, 0x40000, v228
	v_lshlrev_b32_e32 v229, 1, v229
	s_waitcnt vmcnt(15)
	v_cvt_f32_f16_e32 v194, v130
	v_cvt_f32_f16_sdwa v195, v130 dst_sel:DWORD dst_unused:UNUSED_PAD src0_sel:WORD_1
	v_cvt_f32_f16_e32 v196, v131
	v_cvt_f32_f16_sdwa v197, v131 dst_sel:DWORD dst_unused:UNUSED_PAD src0_sel:WORD_1
	v_pk_fma_f32 v[194:195], v[194:195], v[146:147], v[18:19]
	v_pk_fma_f32 v[196:197], v[196:197], v[148:149], v[20:21]
	global_store_dwordx4 v229, v[194:197], s[16:17] offset:512
	s_waitcnt vmcnt(15)
	v_cvt_f32_f16_e32 v198, v132
	v_cvt_f32_f16_sdwa v199, v132 dst_sel:DWORD dst_unused:UNUSED_PAD src0_sel:WORD_1
	v_cvt_f32_f16_e32 v200, v133
	v_cvt_f32_f16_sdwa v201, v133 dst_sel:DWORD dst_unused:UNUSED_PAD src0_sel:WORD_1
	v_pk_fma_f32 v[198:199], v[198:199], v[150:151], v[22:23]
	v_pk_fma_f32 v[200:201], v[200:201], v[152:153], v[24:25]
	global_store_dwordx4 v229, v[198:201], s[16:17] offset:576
	s_waitcnt vmcnt(15)
	v_cvt_f32_f16_e32 v202, v134
	v_cvt_f32_f16_sdwa v203, v134 dst_sel:DWORD dst_unused:UNUSED_PAD src0_sel:WORD_1
	v_cvt_f32_f16_e32 v204, v135
	v_cvt_f32_f16_sdwa v205, v135 dst_sel:DWORD dst_unused:UNUSED_PAD src0_sel:WORD_1
	v_pk_fma_f32 v[202:203], v[202:203], v[154:155], v[26:27]
	v_pk_fma_f32 v[204:205], v[204:205], v[156:157], v[28:29]
	global_store_dwordx4 v229, v[202:205], s[16:17] offset:640
	s_waitcnt vmcnt(15)
	v_cvt_f32_f16_e32 v206, v136
	v_cvt_f32_f16_sdwa v207, v136 dst_sel:DWORD dst_unused:UNUSED_PAD src0_sel:WORD_1
	v_cvt_f32_f16_e32 v208, v137
	v_cvt_f32_f16_sdwa v209, v137 dst_sel:DWORD dst_unused:UNUSED_PAD src0_sel:WORD_1
	v_pk_fma_f32 v[206:207], v[206:207], v[158:159], v[30:31]
	v_pk_fma_f32 v[208:209], v[208:209], v[160:161], v[32:33]
	global_store_dwordx4 v229, v[206:209], s[16:17] offset:704
	v_add_u32_e32 v229, 0x48000, v228
	v_lshlrev_b32_e32 v229, 1, v229
	s_waitcnt vmcnt(15)
	v_cvt_f32_f16_e32 v202, v138
	v_cvt_f32_f16_sdwa v203, v138 dst_sel:DWORD dst_unused:UNUSED_PAD src0_sel:WORD_1
	v_cvt_f32_f16_e32 v204, v139
	v_cvt_f32_f16_sdwa v205, v139 dst_sel:DWORD dst_unused:UNUSED_PAD src0_sel:WORD_1
	v_pk_fma_f32 v[202:203], v[202:203], v[146:147], v[2:3]
	v_pk_fma_f32 v[204:205], v[204:205], v[148:149], v[4:5]
	global_store_dwordx4 v229, v[202:205], s[16:17] offset:512
	s_waitcnt vmcnt(15)
	v_cvt_f32_f16_e32 v206, v140
	v_cvt_f32_f16_sdwa v207, v140 dst_sel:DWORD dst_unused:UNUSED_PAD src0_sel:WORD_1
	v_cvt_f32_f16_e32 v208, v141
	v_cvt_f32_f16_sdwa v209, v141 dst_sel:DWORD dst_unused:UNUSED_PAD src0_sel:WORD_1
	v_pk_fma_f32 v[206:207], v[206:207], v[150:151], v[10:11]
	v_pk_fma_f32 v[208:209], v[208:209], v[152:153], v[12:13]
	global_store_dwordx4 v229, v[206:209], s[16:17] offset:576
	s_waitcnt vmcnt(15)
	v_cvt_f32_f16_e32 v194, v142
	v_cvt_f32_f16_sdwa v195, v142 dst_sel:DWORD dst_unused:UNUSED_PAD src0_sel:WORD_1
	v_cvt_f32_f16_e32 v196, v143
	v_cvt_f32_f16_sdwa v197, v143 dst_sel:DWORD dst_unused:UNUSED_PAD src0_sel:WORD_1
	v_pk_fma_f32 v[194:195], v[194:195], v[154:155], v[6:7]
	v_pk_fma_f32 v[196:197], v[196:197], v[156:157], v[8:9]
	global_store_dwordx4 v229, v[194:197], s[16:17] offset:640
	s_waitcnt vmcnt(15)
	v_cvt_f32_f16_e32 v198, v144
	v_cvt_f32_f16_sdwa v199, v144 dst_sel:DWORD dst_unused:UNUSED_PAD src0_sel:WORD_1
	v_cvt_f32_f16_e32 v200, v145
	v_cvt_f32_f16_sdwa v201, v145 dst_sel:DWORD dst_unused:UNUSED_PAD src0_sel:WORD_1
	v_pk_fma_f32 v[198:199], v[198:199], v[158:159], v[14:15]
	v_pk_fma_f32 v[200:201], v[200:201], v[160:161], v[16:17]
	global_store_dwordx4 v229, v[198:201], s[16:17] offset:704
	s_branch .LBB0_303
